# BO3 + sliver K-loops: closing s_barrier issued before the back-edge / variant-skip branch (loop-edge rotation)
# speedup vs baseline: 1.0013x; 1.0013x over previous
; #define PG8_STAGE(bufoff, gbase, voff) do { _Pragma("unroll") for (int _i = 0; _i < 2; ++_i) \
;         __builtin_amdgcn_global_load_lds((const unsigned*)((const char*)(gbase) + (size_t)_i * qstep + (voff)[0]), (PG8_LAS unsigned*)(lds + (bufoff) + ldsw + _i * 8192), 16, 0, 0); } while (0)
; #define PG8_LDA(dst, b, h) do { _Pragma("unroll") for (int m = 0; m < 4; ++m) _Pragma("unroll") for (int k = 0; k < 2; ++k) dst[m][k] = *(const PG8_LAS bf16x8*)(lds + PG8_SA(b, h) + aoff + m * 2048 + k * 1024); } while (0)
; #define PG8_LDB(dst, b, h) do { _Pragma("unroll") for (int n = 0; n < 2; ++n) _Pragma("unroll") for (int k = 0; k < 2; ++k) dst[n][k] = *(const PG8_LAS bf16x8*)(lds + PG8_SB(b, h) + boff + n * 2048 + k * 1024); } while (0)
; #define PG8_MMA(ai, bj, At, Bt) do { __builtin_amdgcn_s_setprio(1); _Pragma("unroll") for (int m = 0; m < 4; ++m) _Pragma("unroll") for (int n = 0; n < 2; ++n) _Pragma("unroll") for (int k = 0; k < 2; ++k) \
;         acc[ai][bj][m][n] = __builtin_amdgcn_mfma_f32_16x16x32_bf16(Bt[n][k], At[m][k], acc[ai][bj][m][n], 0, 0, 0); __builtin_amdgcn_s_setprio(0); } while (0)
; #define PG8_WAIT_V89() do { if constexpr (SLIVER) PG8_WAIT_V(9); else PG8_WAIT_V(8); } while (0)
; #define PG8_WAIT_L(n) asm volatile("s_waitcnt lgkmcnt(" #n ")" ::: "memory")
; #define PG8_BAR __builtin_amdgcn_s_barrier()
; template <class Epi, class Sched, bool ALIGN_EPI = false, bool SP2 = false, bool SLIVER = false>
; __device__ __forceinline__ void gemm_phase(PG8_LAS unsigned char* lds, const Gemm g, const Sched& S, const Epi& E) {
;     ...
;         for (int t = 0; t < nt; t += 2) {
;             const bool last = (t == nt - 2);
;             const char* a1 = cA + (size_t)(t + 1) * kstep;
;             const char* a2 = last ? nA : cA + (size_t)(t + 2) * kstep; const char* b2 = last ? nB : cB + (size_t)(t + 2) * kstep;
;             const char* a3 = a2 + kstep; const char* b3 = b2 + kstep;
;             const char* s1 = cS + (size_t)(t + 1) * kstep; const char* s2 = last ? nS : cS + (size_t)(t + 2) * kstep;
;             if (last && has_next) S.a_ready(nxt);
;             if constexpr (SP2) {
;             PG8_LDB(B0, 0, 0); PG8_LDB(B1, 0, 1); PG8_SCHED; PG8_LDA(At, 0, 0); PG8_STAGE(PG8_SA(1, 1), a1 + hstep, voffA); PG8_STAGE_S(1, s1);
;             PG8_WAIT_V89(); PG8_WAIT_L(0); PG8_BAR; PG8_MMA(0, 0, At, B0); PG8_MMA(0, 1, At, B1); PG8_BAR; PG8_SCHED;
.LBB0_497:
.Lrot_c0:
	s_mov_b64 s[86:87], 0x4000400
	s_mov_b64 s[88:89], 0x4000800
	s_mov_b64 s[68:69], 0x4000c00
	s_add_i32 s67, s67, 2
	s_add_u32 s80, s80, 0x100
	s_addc_u32 s81, s81, 0
	s_cmp_ge_u32 s67, s3
	s_cbranch_scc1 .LBB0_508
.LBB0_498:
	s_cmp_eq_u32 s66, s80
	s_cselect_b64 s[86:87], -1, 0
	s_add_u32 s40, s16, s80
	s_addc_u32 s41, s17, s81
	s_add_u32 s68, s40, 0x100
	s_addc_u32 s69, s41, 0
	s_and_b64 s[40:41], s[86:87], exec
	s_cselect_b32 s41, s55, s69
	s_cselect_b32 s40, s54, s68
	s_add_u32 s76, s12, s80
	s_addc_u32 s77, s13, s81
	s_add_i32 s78, 0, 0x10000
	s_and_b64 s[68:69], s[86:87], exec
	v_add_u32_e32 v138, s78, v239
	s_cselect_b32 s69, s83, s77
	s_cselect_b32 s68, s82, s76
	s_add_i32 s76, 0, 0x14000
	ds_read_b128 v[146:149], v138
	ds_read_b128 v[150:153], v138 offset:1024
	ds_read_b128 v[154:157], v138 offset:2048
	ds_read_b128 v[158:161], v138 offset:3072
	v_add_u32_e32 v138, s76, v239
	ds_read_b128 v[166:169], v138
	ds_read_b128 v[170:173], v138 offset:1024
	ds_read_b128 v[174:177], v138 offset:2048
	ds_read_b128 v[162:165], v138 offset:3072
	v_lshl_add_u64 v[208:209], v[188:189], 0, s[80:81]
	v_lshl_add_u64 v[224:225], v[208:209], 0, s[34:35]
	s_add_i32 m0, s96, 0xc000
	s_mov_b64 s[88:89], 0x120080
	ds_read_b128 v[138:141], v242
	ds_read_b128 v[142:145], v242 offset:1024
	ds_read_b128 v[180:183], v242 offset:2048
	ds_read_b128 v[184:187], v242 offset:3072
	ds_read_b128 v[192:195], v242 offset:4096
	ds_read_b128 v[196:199], v242 offset:5120
	ds_read_b128 v[200:203], v242 offset:6144
	ds_read_b128 v[220:223], v242 offset:7168
	global_load_lds_dwordx4 v[224:225], off
	v_lshl_add_u64 v[208:209], v[208:209], 0, s[88:89]
	s_add_i32 m0, s96, 0xe000
	s_nop 0
	global_load_lds_dwordx4 v[208:209], off
	v_lshl_add_u64 v[208:209], v[190:191], 0, s[80:81]
	s_add_i32 m0, s94, 0x20800
	s_nop 0
	global_load_lds_dword v[208:209], off
	s_waitcnt vmcnt(9)
	s_waitcnt lgkmcnt(0)
	s_setprio 1
	s_barrier
	v_mfma_f32_16x16x32_bf16 v[134:137], v[146:149], v[138:141], v[134:137]
	v_mfma_f32_16x16x32_bf16 v[134:137], v[150:153], v[142:145], v[134:137]
	v_mfma_f32_16x16x32_bf16 v[130:133], v[158:161], v[142:145], v[130:133]
	v_mfma_f32_16x16x32_bf16 v[130:133], v[154:157], v[138:141], v[130:133]
	v_mfma_f32_16x16x32_bf16 v[122:125], v[154:157], v[180:183], v[122:125]
	v_mfma_f32_16x16x32_bf16 v[122:125], v[158:161], v[184:187], v[122:125]
	v_mfma_f32_16x16x32_bf16 v[126:129], v[150:153], v[184:187], v[126:129]
	v_mfma_f32_16x16x32_bf16 v[126:129], v[146:149], v[180:183], v[126:129]
	v_mfma_f32_16x16x32_bf16 v[118:121], v[146:149], v[192:195], v[118:121]
	v_mfma_f32_16x16x32_bf16 v[118:121], v[150:153], v[196:199], v[118:121]
	v_mfma_f32_16x16x32_bf16 v[114:117], v[158:161], v[196:199], v[114:117]
	v_mfma_f32_16x16x32_bf16 v[114:117], v[154:157], v[192:195], v[114:117]
	v_mfma_f32_16x16x32_bf16 v[106:109], v[154:157], v[200:203], v[106:109]
	v_mfma_f32_16x16x32_bf16 v[106:109], v[158:161], v[220:223], v[106:109]
	v_mfma_f32_16x16x32_bf16 v[110:113], v[150:153], v[220:223], v[110:113]
	v_mfma_f32_16x16x32_bf16 v[110:113], v[146:149], v[200:203], v[110:113]
	s_setprio 0
	s_setprio 1
	v_mfma_f32_16x16x32_bf16 v[66:69], v[174:177], v[200:203], v[66:69]
	v_mfma_f32_16x16x32_bf16 v[66:69], v[162:165], v[220:223], v[66:69]
	v_mfma_f32_16x16x32_bf16 v[98:101], v[162:165], v[142:145], v[98:101]
	v_mfma_f32_16x16x32_bf16 v[98:101], v[174:177], v[138:141], v[98:101]
	v_mfma_f32_16x16x32_bf16 v[102:105], v[166:169], v[138:141], v[102:105]
	v_mfma_f32_16x16x32_bf16 v[102:105], v[170:173], v[142:145], v[102:105]
	v_mfma_f32_16x16x32_bf16 v[90:93], v[170:173], v[184:187], v[90:93]
	v_mfma_f32_16x16x32_bf16 v[90:93], v[166:169], v[180:183], v[90:93]
	v_mfma_f32_16x16x32_bf16 v[86:89], v[174:177], v[180:183], v[86:89]
	v_mfma_f32_16x16x32_bf16 v[86:89], v[162:165], v[184:187], v[86:89]
	v_mfma_f32_16x16x32_bf16 v[74:77], v[162:165], v[196:199], v[74:77]
	v_mfma_f32_16x16x32_bf16 v[74:77], v[174:177], v[192:195], v[74:77]
	v_mfma_f32_16x16x32_bf16 v[78:81], v[166:169], v[192:195], v[78:81]
	v_mfma_f32_16x16x32_bf16 v[78:81], v[170:173], v[196:199], v[78:81]
	v_mfma_f32_16x16x32_bf16 v[70:73], v[170:173], v[220:223], v[70:73]
	v_mfma_f32_16x16x32_bf16 v[70:73], v[166:169], v[200:203], v[70:73]
	s_barrier
; #define PG8_SB(B) __builtin_amdgcn_rcpf(1.f + expneg(B))
; #define PG8_SB(B) __builtin_amdgcn_rcpf(1.f + expneg(B))
; #define PG8_STAGE(bufoff, gbase, voff) do { _Pragma("unroll") for (int _i = 0; _i < 2; ++_i) \
;         __builtin_amdgcn_global_load_lds((const unsigned*)((const char*)(gbase) + (size_t)_i * qstep + (voff)[0]), (PG8_LAS unsigned*)(lds + (bufoff) + ldsw + _i * 8192), 16, 0, 0); } while (0)
; #define PG8_LDA(dst, b, h) do { _Pragma("unroll") for (int m = 0; m < 4; ++m) _Pragma("unroll") for (int k = 0; k < 2; ++k) dst[m][k] = *(const PG8_LAS bf16x8*)(lds + PG8_SA(b, h) + aoff + m * 2048 + k * 1024); } while (0)
; #define PG8_MMA(ai, bj, At, Bt) do { __builtin_amdgcn_s_setprio(1); _Pragma("unroll") for (int m = 0; m < 4; ++m) _Pragma("unroll") for (int n = 0; n < 2; ++n) _Pragma("unroll") for (int k = 0; k < 2; ++k) \
;         acc[ai][bj][m][n] = __builtin_amdgcn_mfma_f32_16x16x32_bf16(Bt[n][k], At[m][k], acc[ai][bj][m][n], 0, 0, 0); __builtin_amdgcn_s_setprio(0); } while (0)
; #define PG8_WAIT_V89() do { if constexpr (SLIVER) PG8_WAIT_V(9); else PG8_WAIT_V(8); } while (0)
; #define PG8_LDS_S(b) do { if constexpr (SLIVER) { Sf[0] = *(const PG8_LAS bf16x8*)(lds + STAGE_BYTES + (b) * 2048 + soff0); Sf[1] = *(const PG8_LAS bf16x8*)(lds + STAGE_BYTES + (b) * 2048 + (soff0 ^ 64)); } } while (0)
; #define PG8_WAIT_L(n) asm volatile("s_waitcnt lgkmcnt(" #n ")" ::: "memory")
; #define PG8_BAR __builtin_amdgcn_s_barrier()
; #define PG8_SCHED __builtin_amdgcn_sched_barrier(0)
; template <class Epi, class Sched, bool ALIGN_EPI = false, bool SP2 = false, bool SLIVER = false>
; __device__ __forceinline__ void gemm_phase(PG8_LAS unsigned char* lds, const Gemm g, const Sched& S, const Epi& E) {
;     ...
;             PG8_LDA(At, 0, 1); PG8_LDS_S(0); PG8_STAGE(PG8_SB(0, 0), b2, voffB); PG8_STAGE(PG8_SB(0, 1), b2 + hstep, voffB); PG8_STAGE(PG8_SA(0, 0), a2, voffA);
;             PG8_WAIT_V89(); PG8_WAIT_L(0); PG8_BAR; PG8_MMA(1, 0, At, B0); PG8_MMA(1, 1, At, B1); PG8_MMA_S(); PG8_BAR; PG8_SCHED;
	s_setprio 0
	s_add_i32 s77, 0, 0x20000
	v_lshl_add_u64 v[192:193], s[68:69], 0, v[212:213]
	s_add_i32 s68, s78, s95
	v_add_u32_e32 v178, s77, v240
	v_add_u32_e32 v184, s77, v241
	s_mov_b32 m0, s68
	s_mov_b64 s[88:89], 0x60000
	ds_read_b128 v[138:141], v242 offset:16384
	ds_read_b128 v[142:145], v242 offset:17408
	ds_read_b128 v[196:199], v242 offset:18432
	ds_read_b128 v[200:203], v242 offset:19456
	ds_read_b128 v[220:223], v242 offset:20480
	ds_read_b128 v[224:227], v242 offset:21504
	ds_read_b128 v[228:231], v242 offset:22528
	ds_read_b128 v[232:235], v242 offset:23552
	ds_read_b128 v[180:183], v178
	ds_read_b128 v[184:187], v184
	global_load_lds_dwordx4 v[192:193], off
	v_lshl_add_u64 v[194:195], v[192:193], 0, s[88:89]
	s_add_i32 m0, s68, 0x2000
	s_add_i32 s68, s76, s95
	global_load_lds_dwordx4 v[194:195], off
	v_lshl_add_u64 v[194:195], v[192:193], 0, s[24:25]
	s_mov_b32 m0, s68
	s_nop 0
	global_load_lds_dwordx4 v[194:195], off
	v_lshl_add_u64 v[194:195], v[192:193], 0, s[14:15]
	s_add_i32 m0, s68, 0x2000
	s_nop 0
	global_load_lds_dwordx4 v[194:195], off
	v_lshl_add_u64 v[194:195], s[40:41], 0, v[210:211]
	s_mov_b32 m0, s96
	v_lshl_add_u64 v[208:209], v[194:195], 0, s[88:89]
	global_load_lds_dwordx4 v[194:195], off
	s_mov_b32 m0, s19
	s_nop 0
	global_load_lds_dwordx4 v[208:209], off
	s_waitcnt vmcnt(9)
	s_waitcnt lgkmcnt(0)
	s_setprio 1
	s_barrier
	v_mfma_f32_16x16x32_bf16 v[62:65], v[146:149], v[138:141], v[62:65]
	v_mfma_f32_16x16x32_bf16 v[62:65], v[150:153], v[142:145], v[62:65]
	v_mfma_f32_16x16x32_bf16 v[58:61], v[158:161], v[142:145], v[58:61]
	v_mfma_f32_16x16x32_bf16 v[58:61], v[154:157], v[138:141], v[58:61]
	v_mfma_f32_16x16x32_bf16 v[50:53], v[154:157], v[196:199], v[50:53]
	v_mfma_f32_16x16x32_bf16 v[50:53], v[158:161], v[200:203], v[50:53]
	v_mfma_f32_16x16x32_bf16 v[54:57], v[150:153], v[200:203], v[54:57]
	v_mfma_f32_16x16x32_bf16 v[54:57], v[146:149], v[196:199], v[54:57]
	v_mfma_f32_16x16x32_bf16 v[46:49], v[146:149], v[220:223], v[46:49]
	v_mfma_f32_16x16x32_bf16 v[46:49], v[150:153], v[224:227], v[46:49]
	v_mfma_f32_16x16x32_bf16 v[42:45], v[158:161], v[224:227], v[42:45]
	v_mfma_f32_16x16x32_bf16 v[42:45], v[154:157], v[220:223], v[42:45]
	v_mfma_f32_16x16x32_bf16 v[34:37], v[154:157], v[228:231], v[34:37]
	v_mfma_f32_16x16x32_bf16 v[34:37], v[158:161], v[232:235], v[34:37]
	v_mfma_f32_16x16x32_bf16 v[38:41], v[150:153], v[232:235], v[38:41]
	v_mfma_f32_16x16x32_bf16 v[38:41], v[146:149], v[228:231], v[38:41]
	s_setprio 0
	s_setprio 1
	v_mfma_f32_16x16x32_bf16 v[2:5], v[174:177], v[228:231], v[2:5]
	v_mfma_f32_16x16x32_bf16 v[2:5], v[162:165], v[232:235], v[2:5]
	v_mfma_f32_16x16x32_bf16 v[26:29], v[162:165], v[142:145], v[26:29]
	v_mfma_f32_16x16x32_bf16 v[26:29], v[174:177], v[138:141], v[26:29]
	v_mfma_f32_16x16x32_bf16 v[30:33], v[166:169], v[138:141], v[30:33]
	v_mfma_f32_16x16x32_bf16 v[30:33], v[170:173], v[142:145], v[30:33]
	v_mfma_f32_16x16x32_bf16 v[22:25], v[170:173], v[200:203], v[22:25]
	v_mfma_f32_16x16x32_bf16 v[22:25], v[166:169], v[196:199], v[22:25]
	v_mfma_f32_16x16x32_bf16 v[18:21], v[174:177], v[196:199], v[18:21]
	v_mfma_f32_16x16x32_bf16 v[18:21], v[162:165], v[200:203], v[18:21]
	v_mfma_f32_16x16x32_bf16 v[10:13], v[162:165], v[224:227], v[10:13]
	v_mfma_f32_16x16x32_bf16 v[10:13], v[174:177], v[220:223], v[10:13]
	v_mfma_f32_16x16x32_bf16 v[14:17], v[166:169], v[220:223], v[14:17]
	v_mfma_f32_16x16x32_bf16 v[14:17], v[170:173], v[224:227], v[14:17]
	v_mfma_f32_16x16x32_bf16 v[6:9], v[170:173], v[232:235], v[6:9]
	v_mfma_f32_16x16x32_bf16 v[6:9], v[166:169], v[228:231], v[6:9]
	s_setprio 0
	s_setprio 1
	s_and_b64 vcc, exec, s[52:53]
	s_cbranch_vccz .Lslv_b0
	v_mfma_f32_16x16x32_bf16 v[138:141], v[166:169], v[180:183], v[82:85]
	v_mfma_f32_16x16x32_bf16 v[142:145], v[174:177], v[180:183], v[94:97]
	v_mfma_f32_16x16x32_bf16 v[138:141], v[170:173], v[184:187], v[138:141]
	v_mfma_f32_16x16x32_bf16 v[142:145], v[162:165], v[184:187], v[142:145]
	s_barrier
	s_setprio 0
	s_branch .Lrot_b0

; #define PG8_STAGE(bufoff, gbase, voff) do { _Pragma("unroll") for (int _i = 0; _i < 2; ++_i) \
;         __builtin_amdgcn_global_load_lds((const unsigned*)((const char*)(gbase) + (size_t)_i * qstep + (voff)[0]), (PG8_LAS unsigned*)(lds + (bufoff) + ldsw + _i * 8192), 16, 0, 0); } while (0)
; #define PG8_LDA(dst, b, h) do { _Pragma("unroll") for (int m = 0; m < 4; ++m) _Pragma("unroll") for (int k = 0; k < 2; ++k) dst[m][k] = *(const PG8_LAS bf16x8*)(lds + PG8_SA(b, h) + aoff + m * 2048 + k * 1024); } while (0)
; #define PG8_LDB(dst, b, h) do { _Pragma("unroll") for (int n = 0; n < 2; ++n) _Pragma("unroll") for (int k = 0; k < 2; ++k) dst[n][k] = *(const PG8_LAS bf16x8*)(lds + PG8_SB(b, h) + boff + n * 2048 + k * 1024); } while (0)
; #define PG8_MMA(ai, bj, At, Bt) do { __builtin_amdgcn_s_setprio(1); _Pragma("unroll") for (int m = 0; m < 4; ++m) _Pragma("unroll") for (int n = 0; n < 2; ++n) _Pragma("unroll") for (int k = 0; k < 2; ++k) \
;         acc[ai][bj][m][n] = __builtin_amdgcn_mfma_f32_16x16x32_bf16(Bt[n][k], At[m][k], acc[ai][bj][m][n], 0, 0, 0); __builtin_amdgcn_s_setprio(0); } while (0)
; #define PG8_WAIT_V89() do { if constexpr (SLIVER) PG8_WAIT_V(9); else PG8_WAIT_V(8); } while (0)
; #define PG8_STAGE_S(b, gbase) do { if constexpr (SLIVER) __builtin_amdgcn_global_load_lds((const unsigned*)((const char*)(gbase) + voffS), (PG8_LAS unsigned*)(lds + STAGE_BYTES + (b) * 2048 + wid * 256), 4, 0, 0); } while (0)
; #define PG8_WAIT_L(n) asm volatile("s_waitcnt lgkmcnt(" #n ")" ::: "memory")
; #define PG8_BAR __builtin_amdgcn_s_barrier()
; #define PG8_SCHED __builtin_amdgcn_sched_barrier(0)
; template <class Epi, class Sched, bool ALIGN_EPI = false, bool SP2 = false, bool SLIVER = false>
; __device__ __forceinline__ void gemm_phase(PG8_LAS unsigned char* lds, const Gemm g, const Sched& S, const Epi& E) {
;     ...
;             PG8_LDB(B0, 1, 0); PG8_LDB(B1, 1, 1); PG8_SCHED; PG8_LDA(At, 1, 0); PG8_STAGE(PG8_SA(0, 1), a2 + hstep, voffA); PG8_STAGE_S(0, s2);
;             PG8_WAIT_V89(); PG8_WAIT_L(0); PG8_BAR; PG8_MMA(0, 0, At, B0); PG8_MMA(0, 1, At, B1); PG8_BAR; PG8_SCHED;
.Lrot_b0:
	s_add_u32 s68, s62, s80
	s_addc_u32 s69, s63, s81
	s_add_u32 s76, s68, 0x100
	s_addc_u32 s77, s69, 0
	s_and_b64 s[68:69], s[86:87], exec
	s_cselect_b32 s69, s85, s77
	s_cselect_b32 s68, s84, s76
	s_add_i32 s76, 0, 0x18000
	v_add_u32_e32 v82, s76, v239
	s_add_i32 s77, 0, 0x1c000
	ds_read_b128 v[146:149], v82
	ds_read_b128 v[150:153], v82 offset:1024
	ds_read_b128 v[154:157], v82 offset:2048
	ds_read_b128 v[158:161], v82 offset:3072
	v_add_u32_e32 v82, s77, v239
	ds_read_b128 v[166:169], v82
	ds_read_b128 v[170:173], v82 offset:1024
	ds_read_b128 v[174:177], v82 offset:2048
	ds_read_b128 v[162:165], v82 offset:3072
	s_mov_b32 m0, s91
	v_lshl_add_u64 v[208:209], v[194:195], 0, s[24:25]
	ds_read_b128 v[82:85], v242 offset:32768
	ds_read_b128 v[94:97], v242 offset:33792
	ds_read_b128 v[180:183], v242 offset:34816
	ds_read_b128 v[184:187], v242 offset:35840
	ds_read_b128 v[196:199], v242 offset:36864
	ds_read_b128 v[200:203], v242 offset:37888
	ds_read_b128 v[220:223], v242 offset:38912
	ds_read_b128 v[224:227], v242 offset:39936
	global_load_lds_dwordx4 v[208:209], off
	v_lshl_add_u64 v[208:209], v[194:195], 0, s[14:15]
	s_mov_b32 m0, s92
	s_nop 0
	global_load_lds_dwordx4 v[208:209], off
	v_lshl_add_u64 v[208:209], s[68:69], 0, v[214:215]
	s_mov_b32 m0, s93
	s_nop 0
	global_load_lds_dword v[208:209], off
	s_waitcnt vmcnt(9)
	s_waitcnt lgkmcnt(0)
	s_setprio 1
	s_barrier
	v_mfma_f32_16x16x32_bf16 v[134:137], v[146:149], v[82:85], v[134:137]
	v_mfma_f32_16x16x32_bf16 v[134:137], v[150:153], v[94:97], v[134:137]
	v_mfma_f32_16x16x32_bf16 v[130:133], v[158:161], v[94:97], v[130:133]
	v_mfma_f32_16x16x32_bf16 v[130:133], v[154:157], v[82:85], v[130:133]
	v_mfma_f32_16x16x32_bf16 v[122:125], v[154:157], v[180:183], v[122:125]
	v_mfma_f32_16x16x32_bf16 v[122:125], v[158:161], v[184:187], v[122:125]
	v_mfma_f32_16x16x32_bf16 v[126:129], v[150:153], v[184:187], v[126:129]
	v_mfma_f32_16x16x32_bf16 v[126:129], v[146:149], v[180:183], v[126:129]
	v_mfma_f32_16x16x32_bf16 v[118:121], v[146:149], v[196:199], v[118:121]
	v_mfma_f32_16x16x32_bf16 v[118:121], v[150:153], v[200:203], v[118:121]
	v_mfma_f32_16x16x32_bf16 v[114:117], v[158:161], v[200:203], v[114:117]
	v_mfma_f32_16x16x32_bf16 v[114:117], v[154:157], v[196:199], v[114:117]
	v_mfma_f32_16x16x32_bf16 v[106:109], v[154:157], v[220:223], v[106:109]
	v_mfma_f32_16x16x32_bf16 v[106:109], v[158:161], v[224:227], v[106:109]
	v_mfma_f32_16x16x32_bf16 v[110:113], v[150:153], v[224:227], v[110:113]
	v_mfma_f32_16x16x32_bf16 v[110:113], v[146:149], v[220:223], v[110:113]
	s_setprio 0
	s_setprio 1
	v_mfma_f32_16x16x32_bf16 v[102:105], v[166:169], v[82:85], v[102:105]
	v_mfma_f32_16x16x32_bf16 v[102:105], v[170:173], v[94:97], v[102:105]
	v_mfma_f32_16x16x32_bf16 v[82:85], v[174:177], v[82:85], v[98:101]
	v_mfma_f32_16x16x32_bf16 v[98:101], v[162:165], v[94:97], v[82:85]
	v_mfma_f32_16x16x32_bf16 v[82:85], v[166:169], v[180:183], v[90:93]
	v_mfma_f32_16x16x32_bf16 v[90:93], v[170:173], v[184:187], v[82:85]
	v_mfma_f32_16x16x32_bf16 v[82:85], v[174:177], v[180:183], v[86:89]
	v_mfma_f32_16x16x32_bf16 v[86:89], v[162:165], v[184:187], v[82:85]
	v_mfma_f32_16x16x32_bf16 v[78:81], v[166:169], v[196:199], v[78:81]
	v_mfma_f32_16x16x32_bf16 v[78:81], v[170:173], v[200:203], v[78:81]
	v_mfma_f32_16x16x32_bf16 v[74:77], v[174:177], v[196:199], v[74:77]
	v_mfma_f32_16x16x32_bf16 v[74:77], v[162:165], v[200:203], v[74:77]
	v_mfma_f32_16x16x32_bf16 v[70:73], v[166:169], v[220:223], v[70:73]
	v_mfma_f32_16x16x32_bf16 v[70:73], v[170:173], v[224:227], v[70:73]
	v_mfma_f32_16x16x32_bf16 v[66:69], v[174:177], v[220:223], v[66:69]
	v_mfma_f32_16x16x32_bf16 v[66:69], v[162:165], v[224:227], v[66:69]
	s_barrier
; #define PG8_SB(B) __builtin_amdgcn_rcpf(1.f + expneg(B))
; #define PG8_SB(B) __builtin_amdgcn_rcpf(1.f + expneg(B))
; #define PG8_STAGE(bufoff, gbase, voff) do { _Pragma("unroll") for (int _i = 0; _i < 2; ++_i) \
;         __builtin_amdgcn_global_load_lds((const unsigned*)((const char*)(gbase) + (size_t)_i * qstep + (voff)[0]), (PG8_LAS unsigned*)(lds + (bufoff) + ldsw + _i * 8192), 16, 0, 0); } while (0)
; #define PG8_LDA(dst, b, h) do { _Pragma("unroll") for (int m = 0; m < 4; ++m) _Pragma("unroll") for (int k = 0; k < 2; ++k) dst[m][k] = *(const PG8_LAS bf16x8*)(lds + PG8_SA(b, h) + aoff + m * 2048 + k * 1024); } while (0)
; #define PG8_MMA(ai, bj, At, Bt) do { __builtin_amdgcn_s_setprio(1); _Pragma("unroll") for (int m = 0; m < 4; ++m) _Pragma("unroll") for (int n = 0; n < 2; ++n) _Pragma("unroll") for (int k = 0; k < 2; ++k) \
;         acc[ai][bj][m][n] = __builtin_amdgcn_mfma_f32_16x16x32_bf16(Bt[n][k], At[m][k], acc[ai][bj][m][n], 0, 0, 0); __builtin_amdgcn_s_setprio(0); } while (0)
; #define PG8_WAIT_V89() do { if constexpr (SLIVER) PG8_WAIT_V(9); else PG8_WAIT_V(8); } while (0)
; #define PG8_LDS_S(b) do { if constexpr (SLIVER) { Sf[0] = *(const PG8_LAS bf16x8*)(lds + STAGE_BYTES + (b) * 2048 + soff0); Sf[1] = *(const PG8_LAS bf16x8*)(lds + STAGE_BYTES + (b) * 2048 + (soff0 ^ 64)); } } while (0)
; #define PG8_WAIT_L(n) asm volatile("s_waitcnt lgkmcnt(" #n ")" ::: "memory")
; #define PG8_BAR __builtin_amdgcn_s_barrier()
; #define PG8_SCHED __builtin_amdgcn_sched_barrier(0)
; template <class Epi, class Sched, bool ALIGN_EPI = false, bool SP2 = false, bool SLIVER = false>
; __device__ __forceinline__ void gemm_phase(PG8_LAS unsigned char* lds, const Gemm g, const Sched& S, const Epi& E) {
;     ...
;             PG8_LDA(At, 1, 1); PG8_LDS_S(1); PG8_STAGE(PG8_SB(1, 0), b3, voffB); PG8_STAGE(PG8_SB(1, 1), b3 + hstep, voffB); PG8_STAGE(PG8_SA(1, 0), a3, voffA);
;             PG8_WAIT_V89(); PG8_WAIT_L(0); PG8_BAR; PG8_MMA(1, 0, At, B0); PG8_MMA(1, 1, At, B1); PG8_MMA_S(); PG8_BAR; PG8_SCHED;
	s_setprio 0
	s_add_i32 s68, 0, 0x20800
	v_add_u32_e32 v178, s68, v240
	v_add_u32_e32 v184, s68, v241
	s_add_i32 s68, s76, s95
	v_lshl_add_u64 v[208:209], v[192:193], 0, s[26:27]
	s_mov_b32 m0, s68
	ds_read_b128 v[82:85], v242 offset:49152
	ds_read_b128 v[94:97], v242 offset:50176
	ds_read_b128 v[196:199], v242 offset:51200
	ds_read_b128 v[200:203], v242 offset:52224
	ds_read_b128 v[220:223], v242 offset:53248
	ds_read_b128 v[224:227], v242 offset:54272
	ds_read_b128 v[228:231], v242 offset:55296
	ds_read_b128 v[232:235], v242 offset:56320
	ds_read_b128 v[180:183], v178
	ds_read_b128 v[184:187], v184
	global_load_lds_dwordx4 v[208:209], off
	v_lshl_add_u64 v[208:209], v[192:193], 0, s[72:73]
	s_add_i32 m0, s68, 0x2000
	s_add_i32 s68, s77, s95
	global_load_lds_dwordx4 v[208:209], off
	v_lshl_add_u64 v[208:209], v[192:193], 0, s[34:35]
	s_mov_b32 m0, s68
	s_mov_b64 s[76:77], 0x120080
	global_load_lds_dwordx4 v[208:209], off
	v_lshl_add_u64 v[192:193], v[192:193], 0, s[76:77]
	s_add_i32 m0, s68, 0x2000
	s_nop 0
	global_load_lds_dwordx4 v[192:193], off
	v_lshl_add_u64 v[192:193], v[194:195], 0, s[26:27]
	s_mov_b32 m0, s97
	s_nop 0
	global_load_lds_dwordx4 v[192:193], off
	v_lshl_add_u64 v[192:193], v[194:195], 0, s[72:73]
	s_mov_b32 m0, s18
	s_nop 0
	global_load_lds_dwordx4 v[192:193], off
	s_waitcnt vmcnt(9)
	s_waitcnt lgkmcnt(0)
	s_setprio 1
	s_barrier
	v_mfma_f32_16x16x32_bf16 v[62:65], v[146:149], v[82:85], v[62:65]
	v_mfma_f32_16x16x32_bf16 v[62:65], v[150:153], v[94:97], v[62:65]
	v_mfma_f32_16x16x32_bf16 v[58:61], v[158:161], v[94:97], v[58:61]
	v_mfma_f32_16x16x32_bf16 v[58:61], v[154:157], v[82:85], v[58:61]
	v_mfma_f32_16x16x32_bf16 v[50:53], v[154:157], v[196:199], v[50:53]
	v_mfma_f32_16x16x32_bf16 v[50:53], v[158:161], v[200:203], v[50:53]
	v_mfma_f32_16x16x32_bf16 v[54:57], v[150:153], v[200:203], v[54:57]
	v_mfma_f32_16x16x32_bf16 v[54:57], v[146:149], v[196:199], v[54:57]
	v_mfma_f32_16x16x32_bf16 v[46:49], v[146:149], v[220:223], v[46:49]
	v_mfma_f32_16x16x32_bf16 v[46:49], v[150:153], v[224:227], v[46:49]
	v_mfma_f32_16x16x32_bf16 v[42:45], v[158:161], v[224:227], v[42:45]
	v_mfma_f32_16x16x32_bf16 v[42:45], v[154:157], v[220:223], v[42:45]
	v_mfma_f32_16x16x32_bf16 v[34:37], v[154:157], v[228:231], v[34:37]
	v_mfma_f32_16x16x32_bf16 v[34:37], v[158:161], v[232:235], v[34:37]
	v_mfma_f32_16x16x32_bf16 v[38:41], v[150:153], v[232:235], v[38:41]
	v_mfma_f32_16x16x32_bf16 v[38:41], v[146:149], v[228:231], v[38:41]
	s_setprio 0
	s_setprio 1
	v_mfma_f32_16x16x32_bf16 v[2:5], v[174:177], v[228:231], v[2:5]
	v_mfma_f32_16x16x32_bf16 v[2:5], v[162:165], v[232:235], v[2:5]
	v_mfma_f32_16x16x32_bf16 v[26:29], v[162:165], v[94:97], v[26:29]
	v_mfma_f32_16x16x32_bf16 v[26:29], v[174:177], v[82:85], v[26:29]
	v_mfma_f32_16x16x32_bf16 v[30:33], v[166:169], v[82:85], v[30:33]
	v_mfma_f32_16x16x32_bf16 v[30:33], v[170:173], v[94:97], v[30:33]
	v_mfma_f32_16x16x32_bf16 v[22:25], v[170:173], v[200:203], v[22:25]
	v_mfma_f32_16x16x32_bf16 v[22:25], v[166:169], v[196:199], v[22:25]
	v_mfma_f32_16x16x32_bf16 v[18:21], v[174:177], v[196:199], v[18:21]
	v_mfma_f32_16x16x32_bf16 v[18:21], v[162:165], v[200:203], v[18:21]
	v_mfma_f32_16x16x32_bf16 v[10:13], v[162:165], v[224:227], v[10:13]
	v_mfma_f32_16x16x32_bf16 v[10:13], v[174:177], v[220:223], v[10:13]
	v_mfma_f32_16x16x32_bf16 v[14:17], v[166:169], v[220:223], v[14:17]
	v_mfma_f32_16x16x32_bf16 v[14:17], v[170:173], v[224:227], v[14:17]
	v_mfma_f32_16x16x32_bf16 v[6:9], v[170:173], v[232:235], v[6:9]
	v_mfma_f32_16x16x32_bf16 v[6:9], v[166:169], v[228:231], v[6:9]
	s_setprio 0
	s_setprio 1
	s_and_b64 vcc, exec, s[52:53]
	s_cbranch_vccz .Lslv_c0
	v_mfma_f32_16x16x32_bf16 v[82:85], v[166:169], v[180:183], v[138:141]
	v_mfma_f32_16x16x32_bf16 v[94:97], v[174:177], v[180:183], v[142:145]
	v_mfma_f32_16x16x32_bf16 v[82:85], v[170:173], v[184:187], v[82:85]
	v_mfma_f32_16x16x32_bf16 v[94:97], v[162:165], v[184:187], v[94:97]
	s_barrier
	s_setprio 0
	s_branch .Lrot_c0
.LBB0_504:
.Lslv_c0:
	v_mfma_f32_16x16x32_bf16 v[82:85], v[146:149], v[180:183], v[138:141]
	v_mfma_f32_16x16x32_bf16 v[94:97], v[154:157], v[180:183], v[142:145]
	v_mfma_f32_16x16x32_bf16 v[82:85], v[150:153], v[184:187], v[82:85]
	v_mfma_f32_16x16x32_bf16 v[94:97], v[158:161], v[184:187], v[94:97]
	s_barrier
	s_setprio 0
	s_branch .Lrot_c0

; #define PG8_STAGE(bufoff, gbase, voff) do { _Pragma("unroll") for (int _i = 0; _i < 2; ++_i) \
;         __builtin_amdgcn_global_load_lds((const unsigned*)((const char*)(gbase) + (size_t)_i * qstep + (voff)[0]), (PG8_LAS unsigned*)(lds + (bufoff) + ldsw + _i * 8192), 16, 0, 0); } while (0)
; #define PG8_LDA(dst, b, h) do { _Pragma("unroll") for (int m = 0; m < 4; ++m) _Pragma("unroll") for (int k = 0; k < 2; ++k) dst[m][k] = *(const PG8_LAS bf16x8*)(lds + PG8_SA(b, h) + aoff + m * 2048 + k * 1024); } while (0)
; #define PG8_LDB(dst, b, h) do { _Pragma("unroll") for (int n = 0; n < 2; ++n) _Pragma("unroll") for (int k = 0; k < 2; ++k) dst[n][k] = *(const PG8_LAS bf16x8*)(lds + PG8_SB(b, h) + boff + n * 2048 + k * 1024); } while (0)
; #define PG8_MMA(ai, bj, At, Bt) do { __builtin_amdgcn_s_setprio(1); _Pragma("unroll") for (int m = 0; m < 4; ++m) _Pragma("unroll") for (int n = 0; n < 2; ++n) _Pragma("unroll") for (int k = 0; k < 2; ++k) \
;         acc[ai][bj][m][n] = __builtin_amdgcn_mfma_f32_16x16x32_bf16(Bt[n][k], At[m][k], acc[ai][bj][m][n], 0, 0, 0); __builtin_amdgcn_s_setprio(0); } while (0)
; #define PG8_WAIT_V89() do { if constexpr (SLIVER) PG8_WAIT_V(9); else PG8_WAIT_V(8); } while (0)
; #define PG8_WAIT_L(n) asm volatile("s_waitcnt lgkmcnt(" #n ")" ::: "memory")
; #define PG8_BAR __builtin_amdgcn_s_barrier()
; template <class Epi, class Sched, bool ALIGN_EPI = false, bool SP2 = false, bool SLIVER = false>
; __device__ __forceinline__ void gemm_phase(PG8_LAS unsigned char* lds, const Gemm g, const Sched& S, const Epi& E) {
;     ...
;         for (int t = 0; t < nt; t += 2) {
;             const bool last = (t == nt - 2);
;             const char* a1 = cA + (size_t)(t + 1) * kstep;
;             const char* a2 = last ? nA : cA + (size_t)(t + 2) * kstep; const char* b2 = last ? nB : cB + (size_t)(t + 2) * kstep;
;             const char* a3 = a2 + kstep; const char* b3 = b2 + kstep;
;             const char* s1 = cS + (size_t)(t + 1) * kstep; const char* s2 = last ? nS : cS + (size_t)(t + 2) * kstep;
;             if (last && has_next) S.a_ready(nxt);
;             if constexpr (SP2) {
;             PG8_LDB(B0, 0, 0); PG8_LDB(B1, 0, 1); PG8_SCHED; PG8_LDA(At, 0, 0); PG8_STAGE(PG8_SA(1, 1), a1 + hstep, voffA); PG8_STAGE_S(1, s1);
;             PG8_WAIT_V89(); PG8_WAIT_L(0); PG8_BAR; PG8_MMA(0, 0, At, B0); PG8_MMA(0, 1, At, B1); PG8_BAR; PG8_SCHED;
.LBB0_597:
.Lrot_c1:
	s_add_i32 s76, s76, 2
	s_add_u32 s62, s62, 0x100
	s_addc_u32 s63, s63, 0
	s_cmp_gt_u32 s76, 29
	s_cbranch_scc1 .LBB0_606
.LBB0_598:
	s_add_u32 s40, s92, s62
	s_addc_u32 s41, s93, s63
	s_add_u32 s77, s40, 0x100
	s_addc_u32 s78, s41, 0
	s_add_u32 s83, s68, s62
	s_addc_u32 s79, s69, s63
	s_add_i32 s96, 0, 0x10000
	s_cmpk_eq_i32 s62, 0xf00
	s_cselect_b64 s[80:81], -1, 0
	s_and_b64 s[40:41], s[80:81], exec
	s_cselect_b32 s41, s12, s78
	s_cselect_b32 s40, s13, s77
	v_add_u32_e32 v138, s96, v212
	s_cselect_b32 s79, s17, s79
	s_cselect_b32 s78, s55, s83
	s_add_i32 s77, 0, 0x14000
	ds_read_b128 v[146:149], v138
	ds_read_b128 v[150:153], v138 offset:1024
	ds_read_b128 v[154:157], v138 offset:2048
	ds_read_b128 v[158:161], v138 offset:3072
	v_add_u32_e32 v138, s77, v212
	ds_read_b128 v[166:169], v138
	ds_read_b128 v[170:173], v138 offset:1024
	ds_read_b128 v[174:177], v138 offset:2048
	ds_read_b128 v[162:165], v138 offset:3072
	v_lshl_add_u64 v[202:203], v[200:201], 0, s[62:63]
	v_lshl_add_u64 v[208:209], v[202:203], 0, s[30:31]
	s_add_i32 m0, s85, 0xc000
	ds_read_b128 v[138:141], v215
	ds_read_b128 v[142:145], v215 offset:1024
	ds_read_b128 v[180:183], v215 offset:2048
	ds_read_b128 v[184:187], v215 offset:3072
	ds_read_b128 v[216:219], v215 offset:4096
	ds_read_b128 v[220:223], v215 offset:5120
	ds_read_b128 v[224:227], v215 offset:6144
	ds_read_b128 v[228:231], v215 offset:7168
	global_load_lds_dwordx4 v[208:209], off
	v_lshl_add_u64 v[202:203], v[202:203], 0, s[34:35]
	s_add_i32 m0, s85, 0xe000
	s_nop 0
	global_load_lds_dwordx4 v[202:203], off
	v_lshl_add_u64 v[202:203], v[198:199], 0, s[62:63]
	s_add_i32 m0, s45, 0x20800
	s_nop 0
	global_load_lds_dword v[202:203], off
	s_waitcnt vmcnt(9)
	s_waitcnt lgkmcnt(0)
	s_setprio 1
	s_barrier
	v_mfma_f32_16x16x32_bf16 v[134:137], v[146:149], v[138:141], v[134:137]
	v_mfma_f32_16x16x32_bf16 v[134:137], v[150:153], v[142:145], v[134:137]
	v_mfma_f32_16x16x32_bf16 v[130:133], v[158:161], v[142:145], v[130:133]
	v_mfma_f32_16x16x32_bf16 v[130:133], v[154:157], v[138:141], v[130:133]
	v_mfma_f32_16x16x32_bf16 v[114:117], v[154:157], v[180:183], v[114:117]
	v_mfma_f32_16x16x32_bf16 v[114:117], v[158:161], v[184:187], v[114:117]
	v_mfma_f32_16x16x32_bf16 v[118:121], v[150:153], v[184:187], v[118:121]
	v_mfma_f32_16x16x32_bf16 v[118:121], v[146:149], v[180:183], v[118:121]
	v_mfma_f32_16x16x32_bf16 v[102:105], v[146:149], v[216:219], v[102:105]
	v_mfma_f32_16x16x32_bf16 v[102:105], v[150:153], v[220:223], v[102:105]
	v_mfma_f32_16x16x32_bf16 v[98:101], v[158:161], v[220:223], v[98:101]
	v_mfma_f32_16x16x32_bf16 v[98:101], v[154:157], v[216:219], v[98:101]
	v_mfma_f32_16x16x32_bf16 v[82:85], v[154:157], v[224:227], v[82:85]
	v_mfma_f32_16x16x32_bf16 v[82:85], v[158:161], v[228:231], v[82:85]
	v_mfma_f32_16x16x32_bf16 v[86:89], v[150:153], v[228:231], v[86:89]
	v_mfma_f32_16x16x32_bf16 v[86:89], v[146:149], v[224:227], v[86:89]
	s_setprio 0
	s_setprio 1
	v_mfma_f32_16x16x32_bf16 v[74:77], v[174:177], v[224:227], v[74:77]
	v_mfma_f32_16x16x32_bf16 v[74:77], v[162:165], v[228:231], v[74:77]
	v_mfma_f32_16x16x32_bf16 v[122:125], v[162:165], v[142:145], v[122:125]
	v_mfma_f32_16x16x32_bf16 v[122:125], v[174:177], v[138:141], v[122:125]
	v_mfma_f32_16x16x32_bf16 v[126:129], v[166:169], v[138:141], v[126:129]
	v_mfma_f32_16x16x32_bf16 v[126:129], v[170:173], v[142:145], v[126:129]
	v_mfma_f32_16x16x32_bf16 v[110:113], v[170:173], v[184:187], v[110:113]
	v_mfma_f32_16x16x32_bf16 v[110:113], v[166:169], v[180:183], v[110:113]
	v_mfma_f32_16x16x32_bf16 v[106:109], v[174:177], v[180:183], v[106:109]
	v_mfma_f32_16x16x32_bf16 v[106:109], v[162:165], v[184:187], v[106:109]
	v_mfma_f32_16x16x32_bf16 v[90:93], v[162:165], v[220:223], v[90:93]
	v_mfma_f32_16x16x32_bf16 v[90:93], v[174:177], v[216:219], v[90:93]
	v_mfma_f32_16x16x32_bf16 v[94:97], v[166:169], v[216:219], v[94:97]
	v_mfma_f32_16x16x32_bf16 v[94:97], v[170:173], v[220:223], v[94:97]
	v_mfma_f32_16x16x32_bf16 v[78:81], v[170:173], v[228:231], v[78:81]
	v_mfma_f32_16x16x32_bf16 v[78:81], v[166:169], v[224:227], v[78:81]
	s_barrier
; #define PG8_SB(B) __builtin_amdgcn_rcpf(1.f + expneg(B))
; #define PG8_SB(B) __builtin_amdgcn_rcpf(1.f + expneg(B))
; #define PG8_STAGE(bufoff, gbase, voff) do { _Pragma("unroll") for (int _i = 0; _i < 2; ++_i) \
;         __builtin_amdgcn_global_load_lds((const unsigned*)((const char*)(gbase) + (size_t)_i * qstep + (voff)[0]), (PG8_LAS unsigned*)(lds + (bufoff) + ldsw + _i * 8192), 16, 0, 0); } while (0)
; #define PG8_LDA(dst, b, h) do { _Pragma("unroll") for (int m = 0; m < 4; ++m) _Pragma("unroll") for (int k = 0; k < 2; ++k) dst[m][k] = *(const PG8_LAS bf16x8*)(lds + PG8_SA(b, h) + aoff + m * 2048 + k * 1024); } while (0)
; #define PG8_MMA(ai, bj, At, Bt) do { __builtin_amdgcn_s_setprio(1); _Pragma("unroll") for (int m = 0; m < 4; ++m) _Pragma("unroll") for (int n = 0; n < 2; ++n) _Pragma("unroll") for (int k = 0; k < 2; ++k) \
;         acc[ai][bj][m][n] = __builtin_amdgcn_mfma_f32_16x16x32_bf16(Bt[n][k], At[m][k], acc[ai][bj][m][n], 0, 0, 0); __builtin_amdgcn_s_setprio(0); } while (0)
; #define PG8_WAIT_V89() do { if constexpr (SLIVER) PG8_WAIT_V(9); else PG8_WAIT_V(8); } while (0)
; #define PG8_LDS_S(b) do { if constexpr (SLIVER) { Sf[0] = *(const PG8_LAS bf16x8*)(lds + STAGE_BYTES + (b) * 2048 + soff0); Sf[1] = *(const PG8_LAS bf16x8*)(lds + STAGE_BYTES + (b) * 2048 + (soff0 ^ 64)); } } while (0)
; #define PG8_WAIT_L(n) asm volatile("s_waitcnt lgkmcnt(" #n ")" ::: "memory")
; #define PG8_BAR __builtin_amdgcn_s_barrier()
; #define PG8_SCHED __builtin_amdgcn_sched_barrier(0)
; template <class Epi, class Sched, bool ALIGN_EPI = false, bool SP2 = false, bool SLIVER = false>
; __device__ __forceinline__ void gemm_phase(PG8_LAS unsigned char* lds, const Gemm g, const Sched& S, const Epi& E) {
;     ...
;             PG8_LDA(At, 0, 1); PG8_LDS_S(0); PG8_STAGE(PG8_SB(0, 0), b2, voffB); PG8_STAGE(PG8_SB(0, 1), b2 + hstep, voffB); PG8_STAGE(PG8_SA(0, 0), a2, voffA);
;             PG8_WAIT_V89(); PG8_WAIT_L(0); PG8_BAR; PG8_MMA(1, 0, At, B0); PG8_MMA(1, 1, At, B1); PG8_MMA_S(); PG8_BAR; PG8_SCHED;
	s_setprio 0
	s_add_i32 s83, 0, 0x20000
	v_lshl_add_u64 v[202:203], s[78:79], 0, v[190:191]
	s_add_i32 s78, s96, s18
	v_add_u32_e32 v178, s83, v213
	v_add_u32_e32 v184, s83, v214
	s_mov_b32 m0, s78
	ds_read_b128 v[138:141], v215 offset:16384
	ds_read_b128 v[142:145], v215 offset:17408
	ds_read_b128 v[216:219], v215 offset:18432
	ds_read_b128 v[220:223], v215 offset:19456
	ds_read_b128 v[224:227], v215 offset:20480
	ds_read_b128 v[228:231], v215 offset:21504
	ds_read_b128 v[232:235], v215 offset:22528
	ds_read_b128 v[240:243], v215 offset:23552
	ds_read_b128 v[180:183], v178
	ds_read_b128 v[184:187], v184
	global_load_lds_dwordx4 v[202:203], off
	v_lshl_add_u64 v[208:209], v[202:203], 0, s[20:21]
	s_add_i32 m0, s78, 0x2000
	s_add_i32 s77, s77, s18
	global_load_lds_dwordx4 v[208:209], off
	v_lshl_add_u64 v[208:209], v[202:203], 0, s[22:23]
	s_mov_b32 m0, s77
	v_lshl_add_u64 v[210:211], s[40:41], 0, v[188:189]
	global_load_lds_dwordx4 v[208:209], off
	v_lshl_add_u64 v[208:209], v[202:203], 0, s[24:25]
	s_add_i32 m0, s77, 0x2000
	s_nop 0
	global_load_lds_dwordx4 v[208:209], off
	s_mov_b32 m0, s85
	v_lshl_add_u64 v[208:209], v[210:211], 0, s[20:21]
	global_load_lds_dwordx4 v[210:211], off
	s_mov_b32 m0, s19
	s_nop 0
	global_load_lds_dwordx4 v[208:209], off
	s_waitcnt vmcnt(9)
	s_waitcnt lgkmcnt(0)
	s_setprio 1
	s_barrier
	v_mfma_f32_16x16x32_bf16 v[70:73], v[146:149], v[138:141], v[70:73]
	v_mfma_f32_16x16x32_bf16 v[70:73], v[150:153], v[142:145], v[70:73]
	v_mfma_f32_16x16x32_bf16 v[66:69], v[158:161], v[142:145], v[66:69]
	v_mfma_f32_16x16x32_bf16 v[66:69], v[154:157], v[138:141], v[66:69]
	v_mfma_f32_16x16x32_bf16 v[50:53], v[154:157], v[216:219], v[50:53]
	v_mfma_f32_16x16x32_bf16 v[50:53], v[158:161], v[220:223], v[50:53]
	v_mfma_f32_16x16x32_bf16 v[54:57], v[150:153], v[220:223], v[54:57]
	v_mfma_f32_16x16x32_bf16 v[54:57], v[146:149], v[216:219], v[54:57]
	v_mfma_f32_16x16x32_bf16 v[38:41], v[146:149], v[224:227], v[38:41]
	v_mfma_f32_16x16x32_bf16 v[38:41], v[150:153], v[228:231], v[38:41]
	v_mfma_f32_16x16x32_bf16 v[34:37], v[158:161], v[228:231], v[34:37]
	v_mfma_f32_16x16x32_bf16 v[34:37], v[154:157], v[224:227], v[34:37]
	v_mfma_f32_16x16x32_bf16 v[18:21], v[154:157], v[232:235], v[18:21]
	v_mfma_f32_16x16x32_bf16 v[18:21], v[158:161], v[240:243], v[18:21]
	v_mfma_f32_16x16x32_bf16 v[22:25], v[150:153], v[240:243], v[22:25]
	v_mfma_f32_16x16x32_bf16 v[22:25], v[146:149], v[232:235], v[22:25]
	s_setprio 0
	s_setprio 1
	v_mfma_f32_16x16x32_bf16 v[10:13], v[174:177], v[232:235], v[10:13]
	v_mfma_f32_16x16x32_bf16 v[10:13], v[162:165], v[240:243], v[10:13]
	v_mfma_f32_16x16x32_bf16 v[58:61], v[162:165], v[142:145], v[58:61]
	v_mfma_f32_16x16x32_bf16 v[58:61], v[174:177], v[138:141], v[58:61]
	v_mfma_f32_16x16x32_bf16 v[62:65], v[166:169], v[138:141], v[62:65]
	v_mfma_f32_16x16x32_bf16 v[62:65], v[170:173], v[142:145], v[62:65]
	v_mfma_f32_16x16x32_bf16 v[46:49], v[170:173], v[220:223], v[46:49]
	v_mfma_f32_16x16x32_bf16 v[46:49], v[166:169], v[216:219], v[46:49]
	v_mfma_f32_16x16x32_bf16 v[42:45], v[174:177], v[216:219], v[42:45]
	v_mfma_f32_16x16x32_bf16 v[42:45], v[162:165], v[220:223], v[42:45]
	v_mfma_f32_16x16x32_bf16 v[26:29], v[162:165], v[228:231], v[26:29]
	v_mfma_f32_16x16x32_bf16 v[26:29], v[174:177], v[224:227], v[26:29]
	v_mfma_f32_16x16x32_bf16 v[30:33], v[166:169], v[224:227], v[30:33]
	v_mfma_f32_16x16x32_bf16 v[30:33], v[170:173], v[228:231], v[30:33]
	v_mfma_f32_16x16x32_bf16 v[14:17], v[170:173], v[240:243], v[14:17]
	v_mfma_f32_16x16x32_bf16 v[14:17], v[166:169], v[232:235], v[14:17]
	s_setprio 0
	s_setprio 1
	s_and_b64 vcc, exec, s[52:53]
	s_cbranch_vccz .Lslv_b1
	v_mfma_f32_16x16x32_bf16 v[138:141], v[166:169], v[180:183], v[6:9]
	v_mfma_f32_16x16x32_bf16 v[142:145], v[174:177], v[180:183], v[2:5]
	v_mfma_f32_16x16x32_bf16 v[138:141], v[170:173], v[184:187], v[138:141]
	v_mfma_f32_16x16x32_bf16 v[142:145], v[162:165], v[184:187], v[142:145]
	s_barrier
	s_setprio 0
	s_branch .Lrot_b1

; #define PG8_STAGE(bufoff, gbase, voff) do { _Pragma("unroll") for (int _i = 0; _i < 2; ++_i) \
;         __builtin_amdgcn_global_load_lds((const unsigned*)((const char*)(gbase) + (size_t)_i * qstep + (voff)[0]), (PG8_LAS unsigned*)(lds + (bufoff) + ldsw + _i * 8192), 16, 0, 0); } while (0)
; #define PG8_LDA(dst, b, h) do { _Pragma("unroll") for (int m = 0; m < 4; ++m) _Pragma("unroll") for (int k = 0; k < 2; ++k) dst[m][k] = *(const PG8_LAS bf16x8*)(lds + PG8_SA(b, h) + aoff + m * 2048 + k * 1024); } while (0)
; #define PG8_LDB(dst, b, h) do { _Pragma("unroll") for (int n = 0; n < 2; ++n) _Pragma("unroll") for (int k = 0; k < 2; ++k) dst[n][k] = *(const PG8_LAS bf16x8*)(lds + PG8_SB(b, h) + boff + n * 2048 + k * 1024); } while (0)
; #define PG8_MMA(ai, bj, At, Bt) do { __builtin_amdgcn_s_setprio(1); _Pragma("unroll") for (int m = 0; m < 4; ++m) _Pragma("unroll") for (int n = 0; n < 2; ++n) _Pragma("unroll") for (int k = 0; k < 2; ++k) \
;         acc[ai][bj][m][n] = __builtin_amdgcn_mfma_f32_16x16x32_bf16(Bt[n][k], At[m][k], acc[ai][bj][m][n], 0, 0, 0); __builtin_amdgcn_s_setprio(0); } while (0)
; #define PG8_WAIT_V89() do { if constexpr (SLIVER) PG8_WAIT_V(9); else PG8_WAIT_V(8); } while (0)
; #define PG8_STAGE_S(b, gbase) do { if constexpr (SLIVER) __builtin_amdgcn_global_load_lds((const unsigned*)((const char*)(gbase) + voffS), (PG8_LAS unsigned*)(lds + STAGE_BYTES + (b) * 2048 + wid * 256), 4, 0, 0); } while (0)
; #define PG8_WAIT_L(n) asm volatile("s_waitcnt lgkmcnt(" #n ")" ::: "memory")
; #define PG8_BAR __builtin_amdgcn_s_barrier()
; #define PG8_SCHED __builtin_amdgcn_sched_barrier(0)
; template <class Epi, class Sched, bool ALIGN_EPI = false, bool SP2 = false, bool SLIVER = false>
; __device__ __forceinline__ void gemm_phase(PG8_LAS unsigned char* lds, const Gemm g, const Sched& S, const Epi& E) {
;     ...
;             PG8_LDB(B0, 1, 0); PG8_LDB(B1, 1, 1); PG8_SCHED; PG8_LDA(At, 1, 0); PG8_STAGE(PG8_SA(0, 1), a2 + hstep, voffA); PG8_STAGE_S(0, s2);
;             PG8_WAIT_V89(); PG8_WAIT_L(0); PG8_BAR; PG8_MMA(0, 0, At, B0); PG8_MMA(0, 1, At, B1); PG8_BAR; PG8_SCHED;
.Lrot_b1:
	s_add_u32 s77, s94, s62
	s_addc_u32 s78, s95, s63
	s_add_u32 s77, s77, 0x100
	s_addc_u32 s83, s78, 0
	s_and_b64 s[78:79], s[80:81], exec
	s_cselect_b32 s79, s66, s83
	s_cselect_b32 s78, s67, s77
	s_add_i32 s77, 0, 0x18000
	v_add_u32_e32 v2, s77, v212
	s_add_i32 s80, 0, 0x1c000
	ds_read_b128 v[146:149], v2
	ds_read_b128 v[150:153], v2 offset:1024
	ds_read_b128 v[154:157], v2 offset:2048
	ds_read_b128 v[158:161], v2 offset:3072
	v_add_u32_e32 v2, s80, v212
	ds_read_b128 v[166:169], v2
	ds_read_b128 v[170:173], v2 offset:1024
	ds_read_b128 v[174:177], v2 offset:2048
	ds_read_b128 v[162:165], v2 offset:3072
	s_mov_b32 m0, s49
	v_lshl_add_u64 v[208:209], v[210:211], 0, s[22:23]
	ds_read_b128 v[2:5], v215 offset:32768
	ds_read_b128 v[6:9], v215 offset:33792
	ds_read_b128 v[180:183], v215 offset:34816
	ds_read_b128 v[184:187], v215 offset:35840
	ds_read_b128 v[216:219], v215 offset:36864
	ds_read_b128 v[220:223], v215 offset:37888
	ds_read_b128 v[224:227], v215 offset:38912
	ds_read_b128 v[228:231], v215 offset:39936
	global_load_lds_dwordx4 v[208:209], off
	v_lshl_add_u64 v[208:209], v[210:211], 0, s[24:25]
	s_mov_b32 m0, s50
	s_nop 0
	global_load_lds_dwordx4 v[208:209], off
	v_lshl_add_u64 v[208:209], s[78:79], 0, v[192:193]
	s_mov_b32 m0, s51
	s_nop 0
	global_load_lds_dword v[208:209], off
	s_waitcnt vmcnt(9)
	s_waitcnt lgkmcnt(0)
	s_setprio 1
	s_barrier
	v_mfma_f32_16x16x32_bf16 v[134:137], v[146:149], v[2:5], v[134:137]
	v_mfma_f32_16x16x32_bf16 v[134:137], v[150:153], v[6:9], v[134:137]
	v_mfma_f32_16x16x32_bf16 v[130:133], v[158:161], v[6:9], v[130:133]
	v_mfma_f32_16x16x32_bf16 v[130:133], v[154:157], v[2:5], v[130:133]
	v_mfma_f32_16x16x32_bf16 v[114:117], v[154:157], v[180:183], v[114:117]
	v_mfma_f32_16x16x32_bf16 v[114:117], v[158:161], v[184:187], v[114:117]
	v_mfma_f32_16x16x32_bf16 v[118:121], v[150:153], v[184:187], v[118:121]
	v_mfma_f32_16x16x32_bf16 v[118:121], v[146:149], v[180:183], v[118:121]
	v_mfma_f32_16x16x32_bf16 v[102:105], v[146:149], v[216:219], v[102:105]
	v_mfma_f32_16x16x32_bf16 v[102:105], v[150:153], v[220:223], v[102:105]
	v_mfma_f32_16x16x32_bf16 v[98:101], v[158:161], v[220:223], v[98:101]
	v_mfma_f32_16x16x32_bf16 v[98:101], v[154:157], v[216:219], v[98:101]
	v_mfma_f32_16x16x32_bf16 v[82:85], v[154:157], v[224:227], v[82:85]
	v_mfma_f32_16x16x32_bf16 v[82:85], v[158:161], v[228:231], v[82:85]
	v_mfma_f32_16x16x32_bf16 v[86:89], v[150:153], v[228:231], v[86:89]
	v_mfma_f32_16x16x32_bf16 v[86:89], v[146:149], v[224:227], v[86:89]
	s_setprio 0
	s_setprio 1
	v_mfma_f32_16x16x32_bf16 v[126:129], v[166:169], v[2:5], v[126:129]
	v_mfma_f32_16x16x32_bf16 v[126:129], v[170:173], v[6:9], v[126:129]
	v_mfma_f32_16x16x32_bf16 v[2:5], v[174:177], v[2:5], v[122:125]
	v_mfma_f32_16x16x32_bf16 v[122:125], v[162:165], v[6:9], v[2:5]
	v_mfma_f32_16x16x32_bf16 v[2:5], v[166:169], v[180:183], v[110:113]
	v_mfma_f32_16x16x32_bf16 v[110:113], v[170:173], v[184:187], v[2:5]
	v_mfma_f32_16x16x32_bf16 v[2:5], v[174:177], v[180:183], v[106:109]
	v_mfma_f32_16x16x32_bf16 v[106:109], v[162:165], v[184:187], v[2:5]
	v_mfma_f32_16x16x32_bf16 v[2:5], v[166:169], v[216:219], v[94:97]
	v_mfma_f32_16x16x32_bf16 v[94:97], v[170:173], v[220:223], v[2:5]
	v_mfma_f32_16x16x32_bf16 v[2:5], v[174:177], v[216:219], v[90:93]
	v_mfma_f32_16x16x32_bf16 v[90:93], v[162:165], v[220:223], v[2:5]
	v_mfma_f32_16x16x32_bf16 v[2:5], v[166:169], v[224:227], v[78:81]
	v_mfma_f32_16x16x32_bf16 v[78:81], v[170:173], v[228:231], v[2:5]
	v_mfma_f32_16x16x32_bf16 v[2:5], v[174:177], v[224:227], v[74:77]
	v_mfma_f32_16x16x32_bf16 v[74:77], v[162:165], v[228:231], v[2:5]
	s_barrier
; #define PG8_SB(B) __builtin_amdgcn_rcpf(1.f + expneg(B))
; #define PG8_SB(B) __builtin_amdgcn_rcpf(1.f + expneg(B))
; #define PG8_STAGE(bufoff, gbase, voff) do { _Pragma("unroll") for (int _i = 0; _i < 2; ++_i) \
;         __builtin_amdgcn_global_load_lds((const unsigned*)((const char*)(gbase) + (size_t)_i * qstep + (voff)[0]), (PG8_LAS unsigned*)(lds + (bufoff) + ldsw + _i * 8192), 16, 0, 0); } while (0)
; #define PG8_LDA(dst, b, h) do { _Pragma("unroll") for (int m = 0; m < 4; ++m) _Pragma("unroll") for (int k = 0; k < 2; ++k) dst[m][k] = *(const PG8_LAS bf16x8*)(lds + PG8_SA(b, h) + aoff + m * 2048 + k * 1024); } while (0)
; #define PG8_MMA(ai, bj, At, Bt) do { __builtin_amdgcn_s_setprio(1); _Pragma("unroll") for (int m = 0; m < 4; ++m) _Pragma("unroll") for (int n = 0; n < 2; ++n) _Pragma("unroll") for (int k = 0; k < 2; ++k) \
;         acc[ai][bj][m][n] = __builtin_amdgcn_mfma_f32_16x16x32_bf16(Bt[n][k], At[m][k], acc[ai][bj][m][n], 0, 0, 0); __builtin_amdgcn_s_setprio(0); } while (0)
; #define PG8_WAIT_V89() do { if constexpr (SLIVER) PG8_WAIT_V(9); else PG8_WAIT_V(8); } while (0)
; #define PG8_LDS_S(b) do { if constexpr (SLIVER) { Sf[0] = *(const PG8_LAS bf16x8*)(lds + STAGE_BYTES + (b) * 2048 + soff0); Sf[1] = *(const PG8_LAS bf16x8*)(lds + STAGE_BYTES + (b) * 2048 + (soff0 ^ 64)); } } while (0)
; #define PG8_WAIT_L(n) asm volatile("s_waitcnt lgkmcnt(" #n ")" ::: "memory")
; #define PG8_BAR __builtin_amdgcn_s_barrier()
; #define PG8_SCHED __builtin_amdgcn_sched_barrier(0)
; template <class Epi, class Sched, bool ALIGN_EPI = false, bool SP2 = false, bool SLIVER = false>
; __device__ __forceinline__ void gemm_phase(PG8_LAS unsigned char* lds, const Gemm g, const Sched& S, const Epi& E) {
;     ...
;             PG8_LDA(At, 1, 1); PG8_LDS_S(1); PG8_STAGE(PG8_SB(1, 0), b3, voffB); PG8_STAGE(PG8_SB(1, 1), b3 + hstep, voffB); PG8_STAGE(PG8_SA(1, 0), a3, voffA);
;             PG8_WAIT_V89(); PG8_WAIT_L(0); PG8_BAR; PG8_MMA(1, 0, At, B0); PG8_MMA(1, 1, At, B1); PG8_MMA_S(); PG8_BAR; PG8_SCHED;
	s_setprio 0
	s_add_i32 s78, 0, 0x20800
	s_add_i32 s77, s77, s18
	v_add_u32_e32 v178, s78, v213
	v_add_u32_e32 v184, s78, v214
	v_lshl_add_u64 v[208:209], v[202:203], 0, s[26:27]
	s_mov_b32 m0, s77
	ds_read_b128 v[2:5], v215 offset:49152
	ds_read_b128 v[6:9], v215 offset:50176
	ds_read_b128 v[216:219], v215 offset:51200
	ds_read_b128 v[220:223], v215 offset:52224
	ds_read_b128 v[224:227], v215 offset:53248
	ds_read_b128 v[228:231], v215 offset:54272
	ds_read_b128 v[232:235], v215 offset:55296
	ds_read_b128 v[240:243], v215 offset:56320
	ds_read_b128 v[180:183], v178
	ds_read_b128 v[184:187], v184
	global_load_lds_dwordx4 v[208:209], off
	v_lshl_add_u64 v[208:209], v[202:203], 0, s[28:29]
	s_add_i32 m0, s77, 0x2000
	s_add_i32 s77, s80, s18
	global_load_lds_dwordx4 v[208:209], off
	v_lshl_add_u64 v[208:209], v[202:203], 0, s[30:31]
	s_mov_b32 m0, s77
	v_lshl_add_u64 v[202:203], v[202:203], 0, s[34:35]
	global_load_lds_dwordx4 v[208:209], off
	s_add_i32 m0, s77, 0x2000
	s_nop 0
	global_load_lds_dwordx4 v[202:203], off
	v_lshl_add_u64 v[202:203], v[210:211], 0, s[26:27]
	s_mov_b32 m0, s10
	s_nop 0
	global_load_lds_dwordx4 v[202:203], off
	v_lshl_add_u64 v[202:203], v[210:211], 0, s[28:29]
	s_mov_b32 m0, s2
	s_nop 0
	global_load_lds_dwordx4 v[202:203], off
	s_waitcnt vmcnt(9)
	s_waitcnt lgkmcnt(0)
	s_setprio 1
	s_barrier
	v_mfma_f32_16x16x32_bf16 v[70:73], v[146:149], v[2:5], v[70:73]
	v_mfma_f32_16x16x32_bf16 v[70:73], v[150:153], v[6:9], v[70:73]
	v_mfma_f32_16x16x32_bf16 v[66:69], v[158:161], v[6:9], v[66:69]
	v_mfma_f32_16x16x32_bf16 v[66:69], v[154:157], v[2:5], v[66:69]
	v_mfma_f32_16x16x32_bf16 v[50:53], v[154:157], v[216:219], v[50:53]
	v_mfma_f32_16x16x32_bf16 v[50:53], v[158:161], v[220:223], v[50:53]
	v_mfma_f32_16x16x32_bf16 v[54:57], v[150:153], v[220:223], v[54:57]
	v_mfma_f32_16x16x32_bf16 v[54:57], v[146:149], v[216:219], v[54:57]
	v_mfma_f32_16x16x32_bf16 v[38:41], v[146:149], v[224:227], v[38:41]
	v_mfma_f32_16x16x32_bf16 v[38:41], v[150:153], v[228:231], v[38:41]
	v_mfma_f32_16x16x32_bf16 v[34:37], v[158:161], v[228:231], v[34:37]
	v_mfma_f32_16x16x32_bf16 v[34:37], v[154:157], v[224:227], v[34:37]
	v_mfma_f32_16x16x32_bf16 v[18:21], v[154:157], v[232:235], v[18:21]
	v_mfma_f32_16x16x32_bf16 v[18:21], v[158:161], v[240:243], v[18:21]
	v_mfma_f32_16x16x32_bf16 v[22:25], v[150:153], v[240:243], v[22:25]
	v_mfma_f32_16x16x32_bf16 v[22:25], v[146:149], v[232:235], v[22:25]
	s_setprio 0
	s_setprio 1
	v_mfma_f32_16x16x32_bf16 v[62:65], v[166:169], v[2:5], v[62:65]
	v_mfma_f32_16x16x32_bf16 v[62:65], v[170:173], v[6:9], v[62:65]
	v_mfma_f32_16x16x32_bf16 v[2:5], v[174:177], v[2:5], v[58:61]
	v_mfma_f32_16x16x32_bf16 v[58:61], v[162:165], v[6:9], v[2:5]
	v_mfma_f32_16x16x32_bf16 v[2:5], v[166:169], v[216:219], v[46:49]
	v_mfma_f32_16x16x32_bf16 v[46:49], v[170:173], v[220:223], v[2:5]
	v_mfma_f32_16x16x32_bf16 v[2:5], v[174:177], v[216:219], v[42:45]
	v_mfma_f32_16x16x32_bf16 v[42:45], v[162:165], v[220:223], v[2:5]
	v_mfma_f32_16x16x32_bf16 v[2:5], v[166:169], v[224:227], v[30:33]
	v_mfma_f32_16x16x32_bf16 v[30:33], v[170:173], v[228:231], v[2:5]
	v_mfma_f32_16x16x32_bf16 v[2:5], v[174:177], v[224:227], v[26:29]
	v_mfma_f32_16x16x32_bf16 v[26:29], v[162:165], v[228:231], v[2:5]
	v_mfma_f32_16x16x32_bf16 v[2:5], v[166:169], v[232:235], v[14:17]
	v_mfma_f32_16x16x32_bf16 v[14:17], v[170:173], v[240:243], v[2:5]
	v_mfma_f32_16x16x32_bf16 v[2:5], v[174:177], v[232:235], v[10:13]
	v_mfma_f32_16x16x32_bf16 v[10:13], v[162:165], v[240:243], v[2:5]
	s_setprio 0
	s_setprio 1
	s_and_b64 vcc, exec, s[52:53]
	s_cbranch_vccz .Lslv_c1
	v_mfma_f32_16x16x32_bf16 v[2:5], v[166:169], v[180:183], v[138:141]
	v_mfma_f32_16x16x32_bf16 v[6:9], v[170:173], v[184:187], v[2:5]
	v_mfma_f32_16x16x32_bf16 v[2:5], v[174:177], v[180:183], v[142:145]
	v_mfma_f32_16x16x32_bf16 v[2:5], v[162:165], v[184:187], v[2:5]
	s_barrier
	s_setprio 0
	s_branch .Lrot_c1
.LBB0_604:
.Lslv_c1:
	v_mfma_f32_16x16x32_bf16 v[2:5], v[146:149], v[180:183], v[138:141]
	v_mfma_f32_16x16x32_bf16 v[6:9], v[150:153], v[184:187], v[2:5]
	v_mfma_f32_16x16x32_bf16 v[2:5], v[154:157], v[180:183], v[142:145]
	v_mfma_f32_16x16x32_bf16 v[2:5], v[158:161], v[184:187], v[2:5]
	s_barrier
	s_setprio 0
	s_branch .Lrot_c1

; #define PG8_STAGE(bufoff, gbase, voff) do { _Pragma("unroll") for (int _i = 0; _i < 2; ++_i) \
;         __builtin_amdgcn_global_load_lds((const unsigned*)((const char*)(gbase) + (size_t)_i * qstep + (voff)[0]), (PG8_LAS unsigned*)(lds + (bufoff) + ldsw + _i * 8192), 16, 0, 0); } while (0)
; #define PG8_LDA(dst, b, h) do { _Pragma("unroll") for (int m = 0; m < 4; ++m) _Pragma("unroll") for (int k = 0; k < 2; ++k) dst[m][k] = *(const PG8_LAS bf16x8*)(lds + PG8_SA(b, h) + aoff + m * 2048 + k * 1024); } while (0)
; #define PG8_LDB(dst, b, h) do { _Pragma("unroll") for (int n = 0; n < 2; ++n) _Pragma("unroll") for (int k = 0; k < 2; ++k) dst[n][k] = *(const PG8_LAS bf16x8*)(lds + PG8_SB(b, h) + boff + n * 2048 + k * 1024); } while (0)
; #define PG8_MMA(ai, bj, At, Bt) do { __builtin_amdgcn_s_setprio(1); _Pragma("unroll") for (int m = 0; m < 4; ++m) _Pragma("unroll") for (int n = 0; n < 2; ++n) _Pragma("unroll") for (int k = 0; k < 2; ++k) \
;         acc[ai][bj][m][n] = __builtin_amdgcn_mfma_f32_16x16x32_bf16(Bt[n][k], At[m][k], acc[ai][bj][m][n], 0, 0, 0); __builtin_amdgcn_s_setprio(0); } while (0)
; #define PG8_WAIT_V89() do { if constexpr (SLIVER) PG8_WAIT_V(9); else PG8_WAIT_V(8); } while (0)
; #define PG8_WAIT_L(n) asm volatile("s_waitcnt lgkmcnt(" #n ")" ::: "memory")
; #define PG8_BAR __builtin_amdgcn_s_barrier()
; template <class Epi, class Sched, bool ALIGN_EPI = false, bool SP2 = false, bool SLIVER = false>
; __device__ __forceinline__ void gemm_phase(PG8_LAS unsigned char* lds, const Gemm g, const Sched& S, const Epi& E) {
;     ...
;         for (int t = 0; t < nt; t += 2) {
;             const bool last = (t == nt - 2);
;             const char* a1 = cA + (size_t)(t + 1) * kstep;
;             const char* a2 = last ? nA : cA + (size_t)(t + 2) * kstep; const char* b2 = last ? nB : cB + (size_t)(t + 2) * kstep;
;             const char* a3 = a2 + kstep; const char* b3 = b2 + kstep;
;             const char* s1 = cS + (size_t)(t + 1) * kstep; const char* s2 = last ? nS : cS + (size_t)(t + 2) * kstep;
;             if (last && has_next) S.a_ready(nxt);
;             if constexpr (SP2) {
;             PG8_LDB(B0, 0, 0); PG8_LDB(B1, 0, 1); PG8_SCHED; PG8_LDA(At, 0, 0); PG8_STAGE(PG8_SA(1, 1), a1 + hstep, voffA); PG8_STAGE_S(1, s1);
;             PG8_WAIT_V89(); PG8_WAIT_L(0); PG8_BAR; PG8_MMA(0, 0, At, B0); PG8_MMA(0, 1, At, B1); PG8_BAR; PG8_SCHED;
.LBB0_810:
.Lrot_c2:
	s_add_i32 s12, s12, 2
	s_add_u32 s62, s62, 0x100
	s_addc_u32 s63, s63, 0
	s_cmpk_gt_u32 s12, 0x55
	s_cbranch_scc1 .LBB0_821
.LBB0_811:
	s_add_u32 s13, s90, s62
	s_addc_u32 s40, s91, s63
	s_add_u32 s13, s13, 0x100
	s_addc_u32 s66, s40, 0
	s_add_u32 s68, s2, s62
	s_addc_u32 s67, s3, s63
	s_add_i32 s69, 0, 0x10000
	s_cmpk_eq_i32 s62, 0x2b00
	s_cselect_b64 s[80:81], -1, 0
	s_and_b64 s[40:41], s[80:81], exec
	s_cselect_b32 s41, s85, s66
	s_cselect_b32 s40, s84, s13
	v_add_u32_e32 v66, s69, v220
	s_cselect_b32 s67, s87, s67
	s_cselect_b32 s66, s86, s68
	s_add_i32 s13, 0, 0x14000
	ds_read_b128 v[154:157], v66
	ds_read_b128 v[158:161], v66 offset:1024
	ds_read_b128 v[162:165], v66 offset:2048
	ds_read_b128 v[174:177], v66 offset:3072
	v_add_u32_e32 v66, s13, v220
	ds_read_b128 v[184:187], v66
	ds_read_b128 v[188:191], v66 offset:1024
	ds_read_b128 v[192:195], v66 offset:2048
	ds_read_b128 v[180:183], v66 offset:3072
	v_lshl_add_u64 v[146:147], v[214:215], 0, s[62:63]
	v_lshl_add_u64 v[148:149], v[146:147], 0, s[8:9]
	s_add_i32 m0, s19, 0xc000
	s_mov_b64 s[94:95], 0x210080
	ds_read_b128 v[66:69], v223
	ds_read_b128 v[70:73], v223 offset:1024
	ds_read_b128 v[74:77], v223 offset:2048
	ds_read_b128 v[78:81], v223 offset:3072
	ds_read_b128 v[216:219], v223 offset:4096
	ds_read_b128 v[224:227], v223 offset:5120
	ds_read_b128 v[228:231], v223 offset:6144
	ds_read_b128 v[232:235], v223 offset:7168
	global_load_lds_dwordx4 v[148:149], off
	v_lshl_add_u64 v[146:147], v[146:147], 0, s[94:95]
	s_add_i32 m0, s19, 0xe000
	s_nop 0
	global_load_lds_dwordx4 v[146:147], off
	v_lshl_add_u64 v[146:147], v[212:213], 0, s[62:63]
	s_add_i32 m0, s96, 0x20800
	s_nop 0
	global_load_lds_dword v[146:147], off
	s_waitcnt vmcnt(9)
	s_waitcnt lgkmcnt(0)
	s_setprio 1
	s_barrier
	v_mfma_f32_16x16x32_bf16 v[146:149], v[154:157], v[66:69], v[170:173]
	v_mfma_f32_16x16x32_bf16 v[146:149], v[158:161], v[70:73], v[146:149]
	v_mfma_f32_16x16x32_bf16 v[150:153], v[162:165], v[66:69], v[166:169]
	v_mfma_f32_16x16x32_bf16 v[150:153], v[174:177], v[70:73], v[150:153]
	v_mfma_f32_16x16x32_bf16 v[134:137], v[154:157], v[74:77], v[134:137]
	v_mfma_f32_16x16x32_bf16 v[134:137], v[158:161], v[78:81], v[134:137]
	v_mfma_f32_16x16x32_bf16 v[130:133], v[162:165], v[74:77], v[130:133]
	v_mfma_f32_16x16x32_bf16 v[130:133], v[174:177], v[78:81], v[130:133]
	v_mfma_f32_16x16x32_bf16 v[118:121], v[154:157], v[216:219], v[118:121]
	v_mfma_f32_16x16x32_bf16 v[118:121], v[158:161], v[224:227], v[118:121]
	v_mfma_f32_16x16x32_bf16 v[114:117], v[162:165], v[216:219], v[114:117]
	v_mfma_f32_16x16x32_bf16 v[114:117], v[174:177], v[224:227], v[114:117]
	v_mfma_f32_16x16x32_bf16 v[102:105], v[154:157], v[228:231], v[102:105]
	v_mfma_f32_16x16x32_bf16 v[102:105], v[158:161], v[232:235], v[102:105]
	v_mfma_f32_16x16x32_bf16 v[98:101], v[162:165], v[228:231], v[98:101]
	v_mfma_f32_16x16x32_bf16 v[98:101], v[174:177], v[232:235], v[98:101]
	s_setprio 0
	s_setprio 1
	v_mfma_f32_16x16x32_bf16 v[142:145], v[184:187], v[66:69], v[142:145]
	v_mfma_f32_16x16x32_bf16 v[142:145], v[188:191], v[70:73], v[142:145]
	v_mfma_f32_16x16x32_bf16 v[66:69], v[192:195], v[66:69], v[138:141]
	v_mfma_f32_16x16x32_bf16 v[138:141], v[180:183], v[70:73], v[66:69]
	v_mfma_f32_16x16x32_bf16 v[66:69], v[184:187], v[74:77], v[126:129]
	v_mfma_f32_16x16x32_bf16 v[126:129], v[188:191], v[78:81], v[66:69]
	v_mfma_f32_16x16x32_bf16 v[66:69], v[192:195], v[74:77], v[122:125]
	v_mfma_f32_16x16x32_bf16 v[122:125], v[180:183], v[78:81], v[66:69]
	v_mfma_f32_16x16x32_bf16 v[66:69], v[184:187], v[216:219], v[110:113]
	v_mfma_f32_16x16x32_bf16 v[110:113], v[188:191], v[224:227], v[66:69]
	v_mfma_f32_16x16x32_bf16 v[66:69], v[192:195], v[216:219], v[106:109]
	v_mfma_f32_16x16x32_bf16 v[106:109], v[180:183], v[224:227], v[66:69]
	v_mfma_f32_16x16x32_bf16 v[66:69], v[184:187], v[228:231], v[94:97]
	v_mfma_f32_16x16x32_bf16 v[94:97], v[188:191], v[232:235], v[66:69]
	v_mfma_f32_16x16x32_bf16 v[66:69], v[192:195], v[228:231], v[90:93]
	v_mfma_f32_16x16x32_bf16 v[90:93], v[180:183], v[232:235], v[66:69]
	s_barrier
; #define PG8_SB(B) __builtin_amdgcn_rcpf(1.f + expneg(B))
; #define PG8_SB(B) __builtin_amdgcn_rcpf(1.f + expneg(B))
; #define PG8_STAGE(bufoff, gbase, voff) do { _Pragma("unroll") for (int _i = 0; _i < 2; ++_i) \
;         __builtin_amdgcn_global_load_lds((const unsigned*)((const char*)(gbase) + (size_t)_i * qstep + (voff)[0]), (PG8_LAS unsigned*)(lds + (bufoff) + ldsw + _i * 8192), 16, 0, 0); } while (0)
; #define PG8_LDA(dst, b, h) do { _Pragma("unroll") for (int m = 0; m < 4; ++m) _Pragma("unroll") for (int k = 0; k < 2; ++k) dst[m][k] = *(const PG8_LAS bf16x8*)(lds + PG8_SA(b, h) + aoff + m * 2048 + k * 1024); } while (0)
; #define PG8_MMA(ai, bj, At, Bt) do { __builtin_amdgcn_s_setprio(1); _Pragma("unroll") for (int m = 0; m < 4; ++m) _Pragma("unroll") for (int n = 0; n < 2; ++n) _Pragma("unroll") for (int k = 0; k < 2; ++k) \
;         acc[ai][bj][m][n] = __builtin_amdgcn_mfma_f32_16x16x32_bf16(Bt[n][k], At[m][k], acc[ai][bj][m][n], 0, 0, 0); __builtin_amdgcn_s_setprio(0); } while (0)
; #define PG8_WAIT_V89() do { if constexpr (SLIVER) PG8_WAIT_V(9); else PG8_WAIT_V(8); } while (0)
; #define PG8_LDS_S(b) do { if constexpr (SLIVER) { Sf[0] = *(const PG8_LAS bf16x8*)(lds + STAGE_BYTES + (b) * 2048 + soff0); Sf[1] = *(const PG8_LAS bf16x8*)(lds + STAGE_BYTES + (b) * 2048 + (soff0 ^ 64)); } } while (0)
; #define PG8_WAIT_L(n) asm volatile("s_waitcnt lgkmcnt(" #n ")" ::: "memory")
; #define PG8_BAR __builtin_amdgcn_s_barrier()
; #define PG8_SCHED __builtin_amdgcn_sched_barrier(0)
; template <class Epi, class Sched, bool ALIGN_EPI = false, bool SP2 = false, bool SLIVER = false>
; __device__ __forceinline__ void gemm_phase(PG8_LAS unsigned char* lds, const Gemm g, const Sched& S, const Epi& E) {
;     ...
;             PG8_LDA(At, 0, 1); PG8_LDS_S(0); PG8_STAGE(PG8_SB(0, 0), b2, voffB); PG8_STAGE(PG8_SB(0, 1), b2 + hstep, voffB); PG8_STAGE(PG8_SA(0, 0), a2, voffA);
;             PG8_WAIT_V89(); PG8_WAIT_L(0); PG8_BAR; PG8_MMA(1, 0, At, B0); PG8_MMA(1, 1, At, B1); PG8_MMA_S(); PG8_BAR; PG8_SCHED;
	s_setprio 0
	s_add_i32 s68, 0, 0x20000
	v_lshl_add_u64 v[216:217], s[66:67], 0, v[198:199]
	s_add_i32 s66, s69, s18
	v_add_u32_e32 v74, s68, v221
	v_add_u32_e32 v75, s68, v222
	s_mov_b32 m0, s66
	ds_read_b128 v[66:69], v223 offset:16384
	ds_read_b128 v[70:73], v223 offset:17408
	ds_read_b128 v[224:227], v223 offset:18432
	ds_read_b128 v[228:231], v223 offset:19456
	ds_read_b128 v[232:235], v223 offset:20480
	ds_read_b128 v[240:243], v223 offset:21504
	ds_read_b128 v[244:247], v223 offset:22528
	ds_read_b128 v[248:251], v223 offset:23552
	ds_read_b128 v[166:169], v74
	ds_read_b128 v[170:173], v75
	global_load_lds_dwordx4 v[216:217], off
	v_lshl_add_u64 v[74:75], v[216:217], 0, s[64:65]
	s_add_i32 m0, s66, 0x2000
	s_add_i32 s13, s13, s18
	global_load_lds_dwordx4 v[74:75], off
	v_lshl_add_u64 v[74:75], v[216:217], 0, s[0:1]
	s_mov_b32 m0, s13
	v_lshl_add_u64 v[218:219], s[40:41], 0, v[196:197]
	global_load_lds_dwordx4 v[74:75], off
	v_lshl_add_u64 v[74:75], v[216:217], 0, s[74:75]
	s_add_i32 m0, s13, 0x2000
	s_nop 0
	global_load_lds_dwordx4 v[74:75], off
	s_mov_b32 m0, s19
	v_lshl_add_u64 v[74:75], v[218:219], 0, s[64:65]
	global_load_lds_dwordx4 v[218:219], off
	s_mov_b32 m0, s52
	s_nop 0
	global_load_lds_dwordx4 v[74:75], off
	s_waitcnt vmcnt(9)
	s_waitcnt lgkmcnt(0)
	s_setprio 1
	s_barrier
	v_mfma_f32_16x16x32_bf16 v[74:77], v[154:157], v[66:69], v[86:89]
	v_mfma_f32_16x16x32_bf16 v[74:77], v[158:161], v[70:73], v[74:77]
	v_mfma_f32_16x16x32_bf16 v[78:81], v[162:165], v[66:69], v[82:85]
	v_mfma_f32_16x16x32_bf16 v[78:81], v[174:177], v[70:73], v[78:81]
	v_mfma_f32_16x16x32_bf16 v[54:57], v[154:157], v[224:227], v[54:57]
	v_mfma_f32_16x16x32_bf16 v[54:57], v[158:161], v[228:231], v[54:57]
	v_mfma_f32_16x16x32_bf16 v[50:53], v[162:165], v[224:227], v[50:53]
	v_mfma_f32_16x16x32_bf16 v[50:53], v[174:177], v[228:231], v[50:53]
	v_mfma_f32_16x16x32_bf16 v[38:41], v[154:157], v[232:235], v[38:41]
	v_mfma_f32_16x16x32_bf16 v[38:41], v[158:161], v[240:243], v[38:41]
	v_mfma_f32_16x16x32_bf16 v[34:37], v[162:165], v[232:235], v[34:37]
	v_mfma_f32_16x16x32_bf16 v[34:37], v[174:177], v[240:243], v[34:37]
	v_mfma_f32_16x16x32_bf16 v[22:25], v[154:157], v[244:247], v[22:25]
	v_mfma_f32_16x16x32_bf16 v[22:25], v[158:161], v[248:251], v[22:25]
	v_mfma_f32_16x16x32_bf16 v[18:21], v[162:165], v[244:247], v[18:21]
	v_mfma_f32_16x16x32_bf16 v[18:21], v[174:177], v[248:251], v[18:21]
	s_setprio 0
	s_setprio 1
	v_mfma_f32_16x16x32_bf16 v[10:13], v[180:183], v[248:251], v[10:13]
	v_mfma_f32_16x16x32_bf16 v[10:13], v[192:195], v[244:247], v[10:13]
	v_mfma_f32_16x16x32_bf16 v[58:61], v[192:195], v[66:69], v[58:61]
	v_mfma_f32_16x16x32_bf16 v[58:61], v[180:183], v[70:73], v[58:61]
	v_mfma_f32_16x16x32_bf16 v[62:65], v[188:191], v[70:73], v[62:65]
	v_mfma_f32_16x16x32_bf16 v[62:65], v[184:187], v[66:69], v[62:65]
	v_mfma_f32_16x16x32_bf16 v[46:49], v[184:187], v[224:227], v[46:49]
	v_mfma_f32_16x16x32_bf16 v[46:49], v[188:191], v[228:231], v[46:49]
	v_mfma_f32_16x16x32_bf16 v[42:45], v[180:183], v[228:231], v[42:45]
	v_mfma_f32_16x16x32_bf16 v[42:45], v[192:195], v[224:227], v[42:45]
	v_mfma_f32_16x16x32_bf16 v[26:29], v[192:195], v[232:235], v[26:29]
	v_mfma_f32_16x16x32_bf16 v[26:29], v[180:183], v[240:243], v[26:29]
	v_mfma_f32_16x16x32_bf16 v[30:33], v[188:191], v[240:243], v[30:33]
	v_mfma_f32_16x16x32_bf16 v[30:33], v[184:187], v[232:235], v[30:33]
	v_mfma_f32_16x16x32_bf16 v[14:17], v[184:187], v[244:247], v[14:17]
	v_mfma_f32_16x16x32_bf16 v[14:17], v[188:191], v[248:251], v[14:17]
	s_setprio 0
	s_setprio 1
	s_and_b64 vcc, exec, s[82:83]
	s_cbranch_vccz .Lslv_b2
	v_mfma_f32_16x16x32_bf16 v[66:69], v[184:187], v[166:169], v[6:9]
	v_mfma_f32_16x16x32_bf16 v[70:73], v[192:195], v[166:169], v[2:5]
	v_mfma_f32_16x16x32_bf16 v[66:69], v[188:191], v[170:173], v[66:69]
	v_mfma_f32_16x16x32_bf16 v[70:73], v[180:183], v[170:173], v[70:73]
	s_barrier
	s_setprio 0
	s_branch .Lrot_b2

; #define PG8_STAGE(bufoff, gbase, voff) do { _Pragma("unroll") for (int _i = 0; _i < 2; ++_i) \
;         __builtin_amdgcn_global_load_lds((const unsigned*)((const char*)(gbase) + (size_t)_i * qstep + (voff)[0]), (PG8_LAS unsigned*)(lds + (bufoff) + ldsw + _i * 8192), 16, 0, 0); } while (0)
; #define PG8_LDA(dst, b, h) do { _Pragma("unroll") for (int m = 0; m < 4; ++m) _Pragma("unroll") for (int k = 0; k < 2; ++k) dst[m][k] = *(const PG8_LAS bf16x8*)(lds + PG8_SA(b, h) + aoff + m * 2048 + k * 1024); } while (0)
; #define PG8_LDB(dst, b, h) do { _Pragma("unroll") for (int n = 0; n < 2; ++n) _Pragma("unroll") for (int k = 0; k < 2; ++k) dst[n][k] = *(const PG8_LAS bf16x8*)(lds + PG8_SB(b, h) + boff + n * 2048 + k * 1024); } while (0)
; #define PG8_MMA(ai, bj, At, Bt) do { __builtin_amdgcn_s_setprio(1); _Pragma("unroll") for (int m = 0; m < 4; ++m) _Pragma("unroll") for (int n = 0; n < 2; ++n) _Pragma("unroll") for (int k = 0; k < 2; ++k) \
;         acc[ai][bj][m][n] = __builtin_amdgcn_mfma_f32_16x16x32_bf16(Bt[n][k], At[m][k], acc[ai][bj][m][n], 0, 0, 0); __builtin_amdgcn_s_setprio(0); } while (0)
; #define PG8_WAIT_V89() do { if constexpr (SLIVER) PG8_WAIT_V(9); else PG8_WAIT_V(8); } while (0)
; #define PG8_STAGE_S(b, gbase) do { if constexpr (SLIVER) __builtin_amdgcn_global_load_lds((const unsigned*)((const char*)(gbase) + voffS), (PG8_LAS unsigned*)(lds + STAGE_BYTES + (b) * 2048 + wid * 256), 4, 0, 0); } while (0)
; #define PG8_WAIT_L(n) asm volatile("s_waitcnt lgkmcnt(" #n ")" ::: "memory")
; #define PG8_BAR __builtin_amdgcn_s_barrier()
; #define PG8_SCHED __builtin_amdgcn_sched_barrier(0)
; template <class Epi, class Sched, bool ALIGN_EPI = false, bool SP2 = false, bool SLIVER = false>
; __device__ __forceinline__ void gemm_phase(PG8_LAS unsigned char* lds, const Gemm g, const Sched& S, const Epi& E) {
;     ...
;             PG8_LDB(B0, 1, 0); PG8_LDB(B1, 1, 1); PG8_SCHED; PG8_LDA(At, 1, 0); PG8_STAGE(PG8_SA(0, 1), a2 + hstep, voffA); PG8_STAGE_S(0, s2);
;             PG8_WAIT_V89(); PG8_WAIT_L(0); PG8_BAR; PG8_MMA(0, 0, At, B0); PG8_MMA(0, 1, At, B1); PG8_BAR; PG8_SCHED;
.Lrot_b2:
	s_add_u32 s13, s92, s62
	s_addc_u32 s66, s93, s63
	s_add_u32 s13, s13, 0x100
	s_addc_u32 s68, s66, 0
	s_and_b64 s[66:67], s[80:81], exec
	s_cselect_b32 s67, s89, s68
	s_cselect_b32 s66, s88, s13
	s_add_i32 s13, 0, 0x18000
	v_add_u32_e32 v2, s13, v220
	s_add_i32 s68, 0, 0x1c000
	ds_read_b128 v[154:157], v2
	ds_read_b128 v[158:161], v2 offset:1024
	ds_read_b128 v[162:165], v2 offset:2048
	ds_read_b128 v[174:177], v2 offset:3072
	v_add_u32_e32 v2, s68, v220
	ds_read_b128 v[184:187], v2
	ds_read_b128 v[188:191], v2 offset:1024
	ds_read_b128 v[192:195], v2 offset:2048
	ds_read_b128 v[180:183], v2 offset:3072
	s_mov_b32 m0, s53
	v_lshl_add_u64 v[166:167], v[218:219], 0, s[0:1]
	ds_read_b128 v[2:5], v223 offset:32768
	ds_read_b128 v[6:9], v223 offset:33792
	ds_read_b128 v[82:85], v223 offset:34816
	ds_read_b128 v[86:89], v223 offset:35840
	ds_read_b128 v[224:227], v223 offset:36864
	ds_read_b128 v[228:231], v223 offset:37888
	ds_read_b128 v[232:235], v223 offset:38912
	ds_read_b128 v[240:243], v223 offset:39936
	global_load_lds_dwordx4 v[166:167], off
	v_lshl_add_u64 v[166:167], v[218:219], 0, s[74:75]
	s_mov_b32 m0, s54
	s_nop 0
	global_load_lds_dwordx4 v[166:167], off
	v_lshl_add_u64 v[166:167], s[66:67], 0, v[200:201]
	s_mov_b32 m0, s55
	s_nop 0
	global_load_lds_dword v[166:167], off
	s_waitcnt vmcnt(9)
	s_waitcnt lgkmcnt(0)
	s_setprio 1
	s_barrier
	v_mfma_f32_16x16x32_bf16 v[146:149], v[154:157], v[2:5], v[146:149]
	v_mfma_f32_16x16x32_bf16 v[170:173], v[158:161], v[6:9], v[146:149]
	v_mfma_f32_16x16x32_bf16 v[146:149], v[162:165], v[2:5], v[150:153]
	v_mfma_f32_16x16x32_bf16 v[166:169], v[174:177], v[6:9], v[146:149]
	v_mfma_f32_16x16x32_bf16 v[134:137], v[154:157], v[82:85], v[134:137]
	v_mfma_f32_16x16x32_bf16 v[134:137], v[158:161], v[86:89], v[134:137]
	v_mfma_f32_16x16x32_bf16 v[130:133], v[162:165], v[82:85], v[130:133]
	v_mfma_f32_16x16x32_bf16 v[130:133], v[174:177], v[86:89], v[130:133]
	v_mfma_f32_16x16x32_bf16 v[118:121], v[154:157], v[224:227], v[118:121]
	v_mfma_f32_16x16x32_bf16 v[118:121], v[158:161], v[228:231], v[118:121]
	v_mfma_f32_16x16x32_bf16 v[114:117], v[162:165], v[224:227], v[114:117]
	v_mfma_f32_16x16x32_bf16 v[114:117], v[174:177], v[228:231], v[114:117]
	v_mfma_f32_16x16x32_bf16 v[102:105], v[154:157], v[232:235], v[102:105]
	v_mfma_f32_16x16x32_bf16 v[102:105], v[158:161], v[240:243], v[102:105]
	v_mfma_f32_16x16x32_bf16 v[98:101], v[162:165], v[232:235], v[98:101]
	v_mfma_f32_16x16x32_bf16 v[98:101], v[174:177], v[240:243], v[98:101]
	s_setprio 0
	s_setprio 1
	v_mfma_f32_16x16x32_bf16 v[142:145], v[184:187], v[2:5], v[142:145]
	v_mfma_f32_16x16x32_bf16 v[142:145], v[188:191], v[6:9], v[142:145]
	v_mfma_f32_16x16x32_bf16 v[2:5], v[192:195], v[2:5], v[138:141]
	v_mfma_f32_16x16x32_bf16 v[138:141], v[180:183], v[6:9], v[2:5]
	v_mfma_f32_16x16x32_bf16 v[2:5], v[184:187], v[82:85], v[126:129]
	v_mfma_f32_16x16x32_bf16 v[126:129], v[188:191], v[86:89], v[2:5]
	v_mfma_f32_16x16x32_bf16 v[2:5], v[192:195], v[82:85], v[122:125]
	v_mfma_f32_16x16x32_bf16 v[122:125], v[180:183], v[86:89], v[2:5]
	v_mfma_f32_16x16x32_bf16 v[2:5], v[184:187], v[224:227], v[110:113]
	v_mfma_f32_16x16x32_bf16 v[110:113], v[188:191], v[228:231], v[2:5]
	v_mfma_f32_16x16x32_bf16 v[2:5], v[192:195], v[224:227], v[106:109]
	v_mfma_f32_16x16x32_bf16 v[106:109], v[180:183], v[228:231], v[2:5]
	v_mfma_f32_16x16x32_bf16 v[2:5], v[184:187], v[232:235], v[94:97]
	v_mfma_f32_16x16x32_bf16 v[94:97], v[188:191], v[240:243], v[2:5]
	v_mfma_f32_16x16x32_bf16 v[2:5], v[192:195], v[232:235], v[90:93]
	v_mfma_f32_16x16x32_bf16 v[90:93], v[180:183], v[240:243], v[2:5]
	s_barrier
; #define PG8_SB(B) __builtin_amdgcn_rcpf(1.f + expneg(B))
; #define PG8_SB(B) __builtin_amdgcn_rcpf(1.f + expneg(B))
; #define PG8_STAGE(bufoff, gbase, voff) do { _Pragma("unroll") for (int _i = 0; _i < 2; ++_i) \
;         __builtin_amdgcn_global_load_lds((const unsigned*)((const char*)(gbase) + (size_t)_i * qstep + (voff)[0]), (PG8_LAS unsigned*)(lds + (bufoff) + ldsw + _i * 8192), 16, 0, 0); } while (0)
; #define PG8_LDA(dst, b, h) do { _Pragma("unroll") for (int m = 0; m < 4; ++m) _Pragma("unroll") for (int k = 0; k < 2; ++k) dst[m][k] = *(const PG8_LAS bf16x8*)(lds + PG8_SA(b, h) + aoff + m * 2048 + k * 1024); } while (0)
; #define PG8_MMA(ai, bj, At, Bt) do { __builtin_amdgcn_s_setprio(1); _Pragma("unroll") for (int m = 0; m < 4; ++m) _Pragma("unroll") for (int n = 0; n < 2; ++n) _Pragma("unroll") for (int k = 0; k < 2; ++k) \
;         acc[ai][bj][m][n] = __builtin_amdgcn_mfma_f32_16x16x32_bf16(Bt[n][k], At[m][k], acc[ai][bj][m][n], 0, 0, 0); __builtin_amdgcn_s_setprio(0); } while (0)
; #define PG8_WAIT_V89() do { if constexpr (SLIVER) PG8_WAIT_V(9); else PG8_WAIT_V(8); } while (0)
; #define PG8_LDS_S(b) do { if constexpr (SLIVER) { Sf[0] = *(const PG8_LAS bf16x8*)(lds + STAGE_BYTES + (b) * 2048 + soff0); Sf[1] = *(const PG8_LAS bf16x8*)(lds + STAGE_BYTES + (b) * 2048 + (soff0 ^ 64)); } } while (0)
; #define PG8_WAIT_L(n) asm volatile("s_waitcnt lgkmcnt(" #n ")" ::: "memory")
; #define PG8_BAR __builtin_amdgcn_s_barrier()
; #define PG8_SCHED __builtin_amdgcn_sched_barrier(0)
; template <class Epi, class Sched, bool ALIGN_EPI = false, bool SP2 = false, bool SLIVER = false>
; __device__ __forceinline__ void gemm_phase(PG8_LAS unsigned char* lds, const Gemm g, const Sched& S, const Epi& E) {
;     ...
;             PG8_LDA(At, 1, 1); PG8_LDS_S(1); PG8_STAGE(PG8_SB(1, 0), b3, voffB); PG8_STAGE(PG8_SB(1, 1), b3 + hstep, voffB); PG8_STAGE(PG8_SA(1, 0), a3, voffA);
;             PG8_WAIT_V89(); PG8_WAIT_L(0); PG8_BAR; PG8_MMA(1, 0, At, B0); PG8_MMA(1, 1, At, B1); PG8_MMA_S(); PG8_BAR; PG8_SCHED;
	s_setprio 0
	s_add_i32 s66, 0, 0x20800
	v_add_u32_e32 v82, s66, v221
	v_add_u32_e32 v83, s66, v222
	s_add_i32 s13, s13, s18
	ds_read_b128 v[2:5], v223 offset:49152
	ds_read_b128 v[6:9], v223 offset:50176
	ds_read_b128 v[224:227], v223 offset:51200
	ds_read_b128 v[228:231], v223 offset:52224
	ds_read_b128 v[232:235], v223 offset:53248
	ds_read_b128 v[240:243], v223 offset:54272
	ds_read_b128 v[244:247], v223 offset:55296
	ds_read_b128 v[248:251], v223 offset:56320
	ds_read_b128 v[146:149], v82
	ds_read_b128 v[150:153], v83
	v_lshl_add_u64 v[82:83], v[216:217], 0, s[26:27]
	s_mov_b32 m0, s13
	s_mov_b64 s[66:67], 0x210080
	global_load_lds_dwordx4 v[82:83], off
	v_lshl_add_u64 v[82:83], v[216:217], 0, s[60:61]
	s_add_i32 m0, s13, 0x2000
	s_add_i32 s13, s68, s18
	global_load_lds_dwordx4 v[82:83], off
	v_lshl_add_u64 v[82:83], v[216:217], 0, s[8:9]
	s_mov_b32 m0, s13
	s_nop 0
	global_load_lds_dwordx4 v[82:83], off
	v_lshl_add_u64 v[82:83], v[216:217], 0, s[66:67]
	s_add_i32 m0, s13, 0x2000
	s_nop 0
	global_load_lds_dwordx4 v[82:83], off
	v_lshl_add_u64 v[82:83], v[218:219], 0, s[26:27]
	s_mov_b32 m0, s10
	s_nop 0
	global_load_lds_dwordx4 v[82:83], off
	v_lshl_add_u64 v[82:83], v[218:219], 0, s[60:61]
	s_mov_b32 m0, s48
	s_nop 0
	global_load_lds_dwordx4 v[82:83], off
	s_waitcnt vmcnt(9)
	s_waitcnt lgkmcnt(0)
	s_setprio 1
	s_barrier
	v_mfma_f32_16x16x32_bf16 v[74:77], v[154:157], v[2:5], v[74:77]
	v_mfma_f32_16x16x32_bf16 v[86:89], v[158:161], v[6:9], v[74:77]
	v_mfma_f32_16x16x32_bf16 v[74:77], v[162:165], v[2:5], v[78:81]
	v_mfma_f32_16x16x32_bf16 v[82:85], v[174:177], v[6:9], v[74:77]
	v_mfma_f32_16x16x32_bf16 v[54:57], v[154:157], v[224:227], v[54:57]
	v_mfma_f32_16x16x32_bf16 v[54:57], v[158:161], v[228:231], v[54:57]
	v_mfma_f32_16x16x32_bf16 v[50:53], v[162:165], v[224:227], v[50:53]
	v_mfma_f32_16x16x32_bf16 v[50:53], v[174:177], v[228:231], v[50:53]
	v_mfma_f32_16x16x32_bf16 v[38:41], v[154:157], v[232:235], v[38:41]
	v_mfma_f32_16x16x32_bf16 v[38:41], v[158:161], v[240:243], v[38:41]
	v_mfma_f32_16x16x32_bf16 v[34:37], v[162:165], v[232:235], v[34:37]
	v_mfma_f32_16x16x32_bf16 v[34:37], v[174:177], v[240:243], v[34:37]
	v_mfma_f32_16x16x32_bf16 v[22:25], v[154:157], v[244:247], v[22:25]
	v_mfma_f32_16x16x32_bf16 v[22:25], v[158:161], v[248:251], v[22:25]
	v_mfma_f32_16x16x32_bf16 v[18:21], v[162:165], v[244:247], v[18:21]
	v_mfma_f32_16x16x32_bf16 v[18:21], v[174:177], v[248:251], v[18:21]
	s_setprio 0
	s_setprio 1
	v_mfma_f32_16x16x32_bf16 v[62:65], v[184:187], v[2:5], v[62:65]
	v_mfma_f32_16x16x32_bf16 v[62:65], v[188:191], v[6:9], v[62:65]
	v_mfma_f32_16x16x32_bf16 v[2:5], v[192:195], v[2:5], v[58:61]
	v_mfma_f32_16x16x32_bf16 v[58:61], v[180:183], v[6:9], v[2:5]
	v_mfma_f32_16x16x32_bf16 v[2:5], v[184:187], v[224:227], v[46:49]
	v_mfma_f32_16x16x32_bf16 v[46:49], v[188:191], v[228:231], v[2:5]
	v_mfma_f32_16x16x32_bf16 v[2:5], v[192:195], v[224:227], v[42:45]
	v_mfma_f32_16x16x32_bf16 v[42:45], v[180:183], v[228:231], v[2:5]
	v_mfma_f32_16x16x32_bf16 v[2:5], v[184:187], v[232:235], v[30:33]
	v_mfma_f32_16x16x32_bf16 v[30:33], v[188:191], v[240:243], v[2:5]
	v_mfma_f32_16x16x32_bf16 v[2:5], v[192:195], v[232:235], v[26:29]
	v_mfma_f32_16x16x32_bf16 v[26:29], v[180:183], v[240:243], v[2:5]
	v_mfma_f32_16x16x32_bf16 v[2:5], v[184:187], v[244:247], v[14:17]
	v_mfma_f32_16x16x32_bf16 v[14:17], v[188:191], v[248:251], v[2:5]
	v_mfma_f32_16x16x32_bf16 v[2:5], v[192:195], v[244:247], v[10:13]
	v_mfma_f32_16x16x32_bf16 v[10:13], v[180:183], v[248:251], v[2:5]
	s_setprio 0
	s_setprio 1
	s_and_b64 vcc, exec, s[82:83]
	s_cbranch_vccz .Lslv_c2
	v_mfma_f32_16x16x32_bf16 v[2:5], v[184:187], v[146:149], v[66:69]
	v_mfma_f32_16x16x32_bf16 v[6:9], v[188:191], v[150:153], v[2:5]
	v_mfma_f32_16x16x32_bf16 v[2:5], v[192:195], v[146:149], v[70:73]
	v_mfma_f32_16x16x32_bf16 v[2:5], v[180:183], v[150:153], v[2:5]
	s_barrier
	s_setprio 0
	s_branch .Lrot_c2
.LBB0_817:
.Lslv_c2:
	v_mfma_f32_16x16x32_bf16 v[2:5], v[154:157], v[146:149], v[66:69]
	v_mfma_f32_16x16x32_bf16 v[6:9], v[158:161], v[150:153], v[2:5]
	v_mfma_f32_16x16x32_bf16 v[2:5], v[162:165], v[146:149], v[70:73]
	v_mfma_f32_16x16x32_bf16 v[2:5], v[174:177], v[150:153], v[2:5]
	s_barrier
	s_setprio 0
	s_branch .Lrot_c2

; #define PG8_STAGE(bufoff, gbase, voff) do { _Pragma("unroll") for (int _i = 0; _i < 2; ++_i) \
;         __builtin_amdgcn_global_load_lds((const unsigned*)((const char*)(gbase) + (size_t)_i * qstep + (voff)[0]), (PG8_LAS unsigned*)(lds + (bufoff) + ldsw + _i * 8192), 16, 0, 0); } while (0)
; #define PG8_LDA(dst, b, h) do { _Pragma("unroll") for (int m = 0; m < 4; ++m) _Pragma("unroll") for (int k = 0; k < 2; ++k) dst[m][k] = *(const PG8_LAS bf16x8*)(lds + PG8_SA(b, h) + aoff + m * 2048 + k * 1024); } while (0)
; #define PG8_LDB(dst, b, h) do { _Pragma("unroll") for (int n = 0; n < 2; ++n) _Pragma("unroll") for (int k = 0; k < 2; ++k) dst[n][k] = *(const PG8_LAS bf16x8*)(lds + PG8_SB(b, h) + boff + n * 2048 + k * 1024); } while (0)
; #define PG8_MMA(ai, bj, At, Bt) do { __builtin_amdgcn_s_setprio(1); _Pragma("unroll") for (int m = 0; m < 4; ++m) _Pragma("unroll") for (int n = 0; n < 2; ++n) _Pragma("unroll") for (int k = 0; k < 2; ++k) \
;         acc[ai][bj][m][n] = __builtin_amdgcn_mfma_f32_16x16x32_bf16(Bt[n][k], At[m][k], acc[ai][bj][m][n], 0, 0, 0); __builtin_amdgcn_s_setprio(0); } while (0)
; #define PG8_WAIT_V89() do { if constexpr (SLIVER) PG8_WAIT_V(9); else PG8_WAIT_V(8); } while (0)
; #define PG8_WAIT_L(n) asm volatile("s_waitcnt lgkmcnt(" #n ")" ::: "memory")
; #define PG8_BAR __builtin_amdgcn_s_barrier()
; template <class Epi, class Sched, bool ALIGN_EPI = false, bool SP2 = false, bool SLIVER = false>
; __device__ __forceinline__ void gemm_phase(PG8_LAS unsigned char* lds, const Gemm g, const Sched& S, const Epi& E) {
;     ...
;         for (int t = 0; t < nt; t += 2) {
;             const bool last = (t == nt - 2);
;             const char* a1 = cA + (size_t)(t + 1) * kstep;
;             const char* a2 = last ? nA : cA + (size_t)(t + 2) * kstep; const char* b2 = last ? nB : cB + (size_t)(t + 2) * kstep;
;             const char* a3 = a2 + kstep; const char* b3 = b2 + kstep;
;             const char* s1 = cS + (size_t)(t + 1) * kstep; const char* s2 = last ? nS : cS + (size_t)(t + 2) * kstep;
;             if (last && has_next) S.a_ready(nxt);
;             if constexpr (SP2) {
;             PG8_LDB(B0, 0, 0); PG8_LDB(B1, 0, 1); PG8_SCHED; PG8_LDA(At, 0, 0); PG8_STAGE(PG8_SA(1, 1), a1 + hstep, voffA); PG8_STAGE_S(1, s1);
;             PG8_WAIT_V89(); PG8_WAIT_L(0); PG8_BAR; PG8_MMA(0, 0, At, B0); PG8_MMA(0, 1, At, B1); PG8_BAR; PG8_SCHED;
.LBB0_933:
.Lrot_c3:
	s_add_i32 s67, s67, 2
	s_add_u32 s62, s62, 0x100
	s_addc_u32 s63, s63, 0
	s_cmp_ge_u32 s67, s2
	s_cbranch_scc1 .LBB0_944
.LBB0_934:
	s_cmp_eq_u32 s66, s62
	s_cselect_b64 s[80:81], -1, 0
	s_add_u32 s12, s42, s62
	s_addc_u32 s13, s43, s63
	s_add_u32 s40, s12, 0x100
	s_addc_u32 s41, s13, 0
	s_and_b64 s[12:13], s[80:81], exec
	s_cselect_b32 s41, s95, s41
	s_cselect_b32 s40, s94, s40
	s_add_u32 s68, s17, s62
	s_addc_u32 s69, s45, s63
	s_add_i32 s76, 0, 0x10000
	s_and_b64 s[12:13], s[80:81], exec
	v_add_u32_e32 v138, s76, v212
	s_cselect_b32 s13, s97, s69
	s_cselect_b32 s12, s96, s68
	s_add_i32 s68, 0, 0x14000
	ds_read_b128 v[146:149], v138
	ds_read_b128 v[150:153], v138 offset:1024
	ds_read_b128 v[154:157], v138 offset:2048
	ds_read_b128 v[158:161], v138 offset:3072
	v_add_u32_e32 v138, s68, v212
	ds_read_b128 v[166:169], v138
	ds_read_b128 v[170:173], v138 offset:1024
	ds_read_b128 v[174:177], v138 offset:2048
	ds_read_b128 v[162:165], v138 offset:3072
	v_lshl_add_u64 v[202:203], v[198:199], 0, s[62:63]
	s_mov_b64 vcc, 0x90080
	v_lshl_add_u64 v[208:209], v[202:203], 0, vcc
	s_add_i32 m0, s93, 0xc000
	s_mov_b64 vcc, 0xd8080
	ds_read_b128 v[138:141], v215
	ds_read_b128 v[142:145], v215 offset:1024
	ds_read_b128 v[180:183], v215 offset:2048
	ds_read_b128 v[184:187], v215 offset:3072
	ds_read_b128 v[216:219], v215 offset:4096
	ds_read_b128 v[220:223], v215 offset:5120
	ds_read_b128 v[224:227], v215 offset:6144
	ds_read_b128 v[228:231], v215 offset:7168
	global_load_lds_dwordx4 v[208:209], off
	v_lshl_add_u64 v[202:203], v[202:203], 0, vcc
	s_add_i32 m0, s93, 0xe000
	s_nop 0
	global_load_lds_dwordx4 v[202:203], off
	v_lshl_add_u64 v[202:203], v[200:201], 0, s[62:63]
	s_add_i32 m0, s50, 0x20800
	s_nop 0
	global_load_lds_dword v[202:203], off
	s_waitcnt vmcnt(9)
	s_waitcnt lgkmcnt(0)
	s_setprio 1
	s_barrier
	v_mfma_f32_16x16x32_bf16 v[134:137], v[146:149], v[138:141], v[134:137]
	v_mfma_f32_16x16x32_bf16 v[134:137], v[150:153], v[142:145], v[134:137]
	v_mfma_f32_16x16x32_bf16 v[130:133], v[158:161], v[142:145], v[130:133]
	v_mfma_f32_16x16x32_bf16 v[130:133], v[154:157], v[138:141], v[130:133]
	v_mfma_f32_16x16x32_bf16 v[122:125], v[154:157], v[180:183], v[122:125]
	v_mfma_f32_16x16x32_bf16 v[122:125], v[158:161], v[184:187], v[122:125]
	v_mfma_f32_16x16x32_bf16 v[126:129], v[150:153], v[184:187], v[126:129]
	v_mfma_f32_16x16x32_bf16 v[126:129], v[146:149], v[180:183], v[126:129]
	v_mfma_f32_16x16x32_bf16 v[114:117], v[146:149], v[216:219], v[114:117]
	v_mfma_f32_16x16x32_bf16 v[114:117], v[150:153], v[220:223], v[114:117]
	v_mfma_f32_16x16x32_bf16 v[106:109], v[158:161], v[220:223], v[106:109]
	v_mfma_f32_16x16x32_bf16 v[106:109], v[154:157], v[216:219], v[106:109]
	v_mfma_f32_16x16x32_bf16 v[90:93], v[154:157], v[224:227], v[90:93]
	v_mfma_f32_16x16x32_bf16 v[90:93], v[158:161], v[228:231], v[90:93]
	v_mfma_f32_16x16x32_bf16 v[98:101], v[150:153], v[228:231], v[98:101]
	v_mfma_f32_16x16x32_bf16 v[98:101], v[146:149], v[224:227], v[98:101]
	s_setprio 0
	s_setprio 1
	v_mfma_f32_16x16x32_bf16 v[74:77], v[174:177], v[224:227], v[74:77]
	v_mfma_f32_16x16x32_bf16 v[74:77], v[162:165], v[228:231], v[74:77]
	v_mfma_f32_16x16x32_bf16 v[110:113], v[162:165], v[142:145], v[110:113]
	v_mfma_f32_16x16x32_bf16 v[110:113], v[174:177], v[138:141], v[110:113]
	v_mfma_f32_16x16x32_bf16 v[118:121], v[166:169], v[138:141], v[118:121]
	v_mfma_f32_16x16x32_bf16 v[118:121], v[170:173], v[142:145], v[118:121]
	v_mfma_f32_16x16x32_bf16 v[102:105], v[170:173], v[184:187], v[102:105]
	v_mfma_f32_16x16x32_bf16 v[102:105], v[166:169], v[180:183], v[102:105]
	v_mfma_f32_16x16x32_bf16 v[94:97], v[174:177], v[180:183], v[94:97]
	v_mfma_f32_16x16x32_bf16 v[94:97], v[162:165], v[184:187], v[94:97]
	v_mfma_f32_16x16x32_bf16 v[82:85], v[162:165], v[220:223], v[82:85]
	v_mfma_f32_16x16x32_bf16 v[82:85], v[174:177], v[216:219], v[82:85]
	v_mfma_f32_16x16x32_bf16 v[86:89], v[166:169], v[216:219], v[86:89]
	v_mfma_f32_16x16x32_bf16 v[86:89], v[170:173], v[220:223], v[86:89]
	v_mfma_f32_16x16x32_bf16 v[78:81], v[170:173], v[228:231], v[78:81]
	v_mfma_f32_16x16x32_bf16 v[78:81], v[166:169], v[224:227], v[78:81]
	s_barrier
; #define PG8_SB(B) __builtin_amdgcn_rcpf(1.f + expneg(B))
; #define PG8_SB(B) __builtin_amdgcn_rcpf(1.f + expneg(B))
; #define PG8_STAGE(bufoff, gbase, voff) do { _Pragma("unroll") for (int _i = 0; _i < 2; ++_i) \
;         __builtin_amdgcn_global_load_lds((const unsigned*)((const char*)(gbase) + (size_t)_i * qstep + (voff)[0]), (PG8_LAS unsigned*)(lds + (bufoff) + ldsw + _i * 8192), 16, 0, 0); } while (0)
; #define PG8_LDA(dst, b, h) do { _Pragma("unroll") for (int m = 0; m < 4; ++m) _Pragma("unroll") for (int k = 0; k < 2; ++k) dst[m][k] = *(const PG8_LAS bf16x8*)(lds + PG8_SA(b, h) + aoff + m * 2048 + k * 1024); } while (0)
; #define PG8_MMA(ai, bj, At, Bt) do { __builtin_amdgcn_s_setprio(1); _Pragma("unroll") for (int m = 0; m < 4; ++m) _Pragma("unroll") for (int n = 0; n < 2; ++n) _Pragma("unroll") for (int k = 0; k < 2; ++k) \
;         acc[ai][bj][m][n] = __builtin_amdgcn_mfma_f32_16x16x32_bf16(Bt[n][k], At[m][k], acc[ai][bj][m][n], 0, 0, 0); __builtin_amdgcn_s_setprio(0); } while (0)
; #define PG8_WAIT_V89() do { if constexpr (SLIVER) PG8_WAIT_V(9); else PG8_WAIT_V(8); } while (0)
; #define PG8_LDS_S(b) do { if constexpr (SLIVER) { Sf[0] = *(const PG8_LAS bf16x8*)(lds + STAGE_BYTES + (b) * 2048 + soff0); Sf[1] = *(const PG8_LAS bf16x8*)(lds + STAGE_BYTES + (b) * 2048 + (soff0 ^ 64)); } } while (0)
; #define PG8_WAIT_L(n) asm volatile("s_waitcnt lgkmcnt(" #n ")" ::: "memory")
; #define PG8_BAR __builtin_amdgcn_s_barrier()
; #define PG8_SCHED __builtin_amdgcn_sched_barrier(0)
; template <class Epi, class Sched, bool ALIGN_EPI = false, bool SP2 = false, bool SLIVER = false>
; __device__ __forceinline__ void gemm_phase(PG8_LAS unsigned char* lds, const Gemm g, const Sched& S, const Epi& E) {
;     ...
;             PG8_LDA(At, 0, 1); PG8_LDS_S(0); PG8_STAGE(PG8_SB(0, 0), b2, voffB); PG8_STAGE(PG8_SB(0, 1), b2 + hstep, voffB); PG8_STAGE(PG8_SA(0, 0), a2, voffA);
;             PG8_WAIT_V89(); PG8_WAIT_L(0); PG8_BAR; PG8_MMA(1, 0, At, B0); PG8_MMA(1, 1, At, B1); PG8_MMA_S(); PG8_BAR; PG8_SCHED;
	s_setprio 0
	s_add_i32 s69, 0, 0x20000
	v_lshl_add_u64 v[202:203], s[12:13], 0, v[190:191]
	s_add_i32 s12, s76, s92
	v_add_u32_e32 v178, s69, v213
	v_add_u32_e32 v184, s69, v214
	s_mov_b32 m0, s12
	ds_read_b128 v[138:141], v215 offset:16384
	ds_read_b128 v[142:145], v215 offset:17408
	ds_read_b128 v[216:219], v215 offset:18432
	ds_read_b128 v[220:223], v215 offset:19456
	ds_read_b128 v[224:227], v215 offset:20480
	ds_read_b128 v[228:231], v215 offset:21504
	ds_read_b128 v[232:235], v215 offset:22528
	ds_read_b128 v[240:243], v215 offset:23552
	ds_read_b128 v[180:183], v178
	ds_read_b128 v[184:187], v184
	global_load_lds_dwordx4 v[202:203], off
	v_lshl_add_u64 v[208:209], v[202:203], 0, s[70:71]
	s_add_i32 m0, s12, 0x2000
	s_add_i32 s12, s68, s92
	global_load_lds_dwordx4 v[208:209], off
	v_lshl_add_u64 v[208:209], v[202:203], 0, s[46:47]
	s_mov_b32 m0, s12
	v_lshl_add_u64 v[210:211], s[40:41], 0, v[188:189]
	global_load_lds_dwordx4 v[208:209], off
	v_lshl_add_u64 v[208:209], v[202:203], 0, s[6:7]
	s_add_i32 m0, s12, 0x2000
	s_nop 0
	global_load_lds_dwordx4 v[208:209], off
	s_mov_b32 m0, s93
	v_lshl_add_u64 v[208:209], v[210:211], 0, s[70:71]
	global_load_lds_dwordx4 v[210:211], off
	s_mov_b32 m0, s48
	s_nop 0
	global_load_lds_dwordx4 v[208:209], off
	s_waitcnt vmcnt(9)
	s_waitcnt lgkmcnt(0)
	s_setprio 1
	s_barrier
	v_mfma_f32_16x16x32_bf16 v[70:73], v[146:149], v[138:141], v[70:73]
	v_mfma_f32_16x16x32_bf16 v[70:73], v[150:153], v[142:145], v[70:73]
	v_mfma_f32_16x16x32_bf16 v[66:69], v[158:161], v[142:145], v[66:69]
	v_mfma_f32_16x16x32_bf16 v[66:69], v[154:157], v[138:141], v[66:69]
	v_mfma_f32_16x16x32_bf16 v[58:61], v[154:157], v[216:219], v[58:61]
	v_mfma_f32_16x16x32_bf16 v[58:61], v[158:161], v[220:223], v[58:61]
	v_mfma_f32_16x16x32_bf16 v[62:65], v[150:153], v[220:223], v[62:65]
	v_mfma_f32_16x16x32_bf16 v[62:65], v[146:149], v[216:219], v[62:65]
	v_mfma_f32_16x16x32_bf16 v[50:53], v[146:149], v[224:227], v[50:53]
	v_mfma_f32_16x16x32_bf16 v[50:53], v[150:153], v[228:231], v[50:53]
	v_mfma_f32_16x16x32_bf16 v[42:45], v[158:161], v[228:231], v[42:45]
	v_mfma_f32_16x16x32_bf16 v[42:45], v[154:157], v[224:227], v[42:45]
	v_mfma_f32_16x16x32_bf16 v[26:29], v[154:157], v[232:235], v[26:29]
	v_mfma_f32_16x16x32_bf16 v[26:29], v[158:161], v[240:243], v[26:29]
	v_mfma_f32_16x16x32_bf16 v[34:37], v[150:153], v[240:243], v[34:37]
	v_mfma_f32_16x16x32_bf16 v[34:37], v[146:149], v[232:235], v[34:37]
	s_setprio 0
	s_setprio 1
	v_mfma_f32_16x16x32_bf16 v[10:13], v[174:177], v[232:235], v[10:13]
	v_mfma_f32_16x16x32_bf16 v[10:13], v[162:165], v[240:243], v[10:13]
	v_mfma_f32_16x16x32_bf16 v[46:49], v[162:165], v[142:145], v[46:49]
	v_mfma_f32_16x16x32_bf16 v[46:49], v[174:177], v[138:141], v[46:49]
	v_mfma_f32_16x16x32_bf16 v[54:57], v[166:169], v[138:141], v[54:57]
	v_mfma_f32_16x16x32_bf16 v[54:57], v[170:173], v[142:145], v[54:57]
	v_mfma_f32_16x16x32_bf16 v[38:41], v[170:173], v[220:223], v[38:41]
	v_mfma_f32_16x16x32_bf16 v[38:41], v[166:169], v[216:219], v[38:41]
	v_mfma_f32_16x16x32_bf16 v[30:33], v[174:177], v[216:219], v[30:33]
	v_mfma_f32_16x16x32_bf16 v[30:33], v[162:165], v[220:223], v[30:33]
	v_mfma_f32_16x16x32_bf16 v[18:21], v[162:165], v[228:231], v[18:21]
	v_mfma_f32_16x16x32_bf16 v[18:21], v[174:177], v[224:227], v[18:21]
	v_mfma_f32_16x16x32_bf16 v[22:25], v[166:169], v[224:227], v[22:25]
	v_mfma_f32_16x16x32_bf16 v[22:25], v[170:173], v[228:231], v[22:25]
	v_mfma_f32_16x16x32_bf16 v[14:17], v[170:173], v[240:243], v[14:17]
	v_mfma_f32_16x16x32_bf16 v[14:17], v[166:169], v[232:235], v[14:17]
	s_setprio 0
	s_setprio 1
	s_and_b64 vcc, exec, s[90:91]
	s_cbranch_vccz .Lslv_b3
	v_mfma_f32_16x16x32_bf16 v[138:141], v[166:169], v[180:183], v[6:9]
	v_mfma_f32_16x16x32_bf16 v[142:145], v[174:177], v[180:183], v[2:5]
	v_mfma_f32_16x16x32_bf16 v[138:141], v[170:173], v[184:187], v[138:141]
	v_mfma_f32_16x16x32_bf16 v[142:145], v[162:165], v[184:187], v[142:145]
	s_barrier
	s_setprio 0
	s_branch .Lrot_b3

; #define PG8_STAGE(bufoff, gbase, voff) do { _Pragma("unroll") for (int _i = 0; _i < 2; ++_i) \
;         __builtin_amdgcn_global_load_lds((const unsigned*)((const char*)(gbase) + (size_t)_i * qstep + (voff)[0]), (PG8_LAS unsigned*)(lds + (bufoff) + ldsw + _i * 8192), 16, 0, 0); } while (0)
; #define PG8_LDA(dst, b, h) do { _Pragma("unroll") for (int m = 0; m < 4; ++m) _Pragma("unroll") for (int k = 0; k < 2; ++k) dst[m][k] = *(const PG8_LAS bf16x8*)(lds + PG8_SA(b, h) + aoff + m * 2048 + k * 1024); } while (0)
; #define PG8_LDB(dst, b, h) do { _Pragma("unroll") for (int n = 0; n < 2; ++n) _Pragma("unroll") for (int k = 0; k < 2; ++k) dst[n][k] = *(const PG8_LAS bf16x8*)(lds + PG8_SB(b, h) + boff + n * 2048 + k * 1024); } while (0)
; #define PG8_MMA(ai, bj, At, Bt) do { __builtin_amdgcn_s_setprio(1); _Pragma("unroll") for (int m = 0; m < 4; ++m) _Pragma("unroll") for (int n = 0; n < 2; ++n) _Pragma("unroll") for (int k = 0; k < 2; ++k) \
;         acc[ai][bj][m][n] = __builtin_amdgcn_mfma_f32_16x16x32_bf16(Bt[n][k], At[m][k], acc[ai][bj][m][n], 0, 0, 0); __builtin_amdgcn_s_setprio(0); } while (0)
; #define PG8_WAIT_V89() do { if constexpr (SLIVER) PG8_WAIT_V(9); else PG8_WAIT_V(8); } while (0)
; #define PG8_STAGE_S(b, gbase) do { if constexpr (SLIVER) __builtin_amdgcn_global_load_lds((const unsigned*)((const char*)(gbase) + voffS), (PG8_LAS unsigned*)(lds + STAGE_BYTES + (b) * 2048 + wid * 256), 4, 0, 0); } while (0)
; #define PG8_WAIT_L(n) asm volatile("s_waitcnt lgkmcnt(" #n ")" ::: "memory")
; #define PG8_BAR __builtin_amdgcn_s_barrier()
; #define PG8_SCHED __builtin_amdgcn_sched_barrier(0)
; template <class Epi, class Sched, bool ALIGN_EPI = false, bool SP2 = false, bool SLIVER = false>
; __device__ __forceinline__ void gemm_phase(PG8_LAS unsigned char* lds, const Gemm g, const Sched& S, const Epi& E) {
;     ...
;             PG8_LDB(B0, 1, 0); PG8_LDB(B1, 1, 1); PG8_SCHED; PG8_LDA(At, 1, 0); PG8_STAGE(PG8_SA(0, 1), a2 + hstep, voffA); PG8_STAGE_S(0, s2);
;             PG8_WAIT_V89(); PG8_WAIT_L(0); PG8_BAR; PG8_MMA(0, 0, At, B0); PG8_MMA(0, 1, At, B1); PG8_BAR; PG8_SCHED;
.Lrot_b3:
	s_add_u32 s12, s54, s62
	s_addc_u32 s13, s55, s63
	s_add_u32 s68, s12, 0x100
	s_addc_u32 s69, s13, 0
	s_and_b64 s[12:13], s[80:81], exec
	s_cselect_b32 s13, s19, s69
	s_cselect_b32 s12, s18, s68
	s_add_i32 s68, 0, 0x18000
	v_add_u32_e32 v2, s68, v212
	s_add_i32 s69, 0, 0x1c000
	ds_read_b128 v[146:149], v2
	ds_read_b128 v[150:153], v2 offset:1024
	ds_read_b128 v[154:157], v2 offset:2048
	ds_read_b128 v[158:161], v2 offset:3072
	v_add_u32_e32 v2, s69, v212
	ds_read_b128 v[166:169], v2
	ds_read_b128 v[170:173], v2 offset:1024
	ds_read_b128 v[174:177], v2 offset:2048
	ds_read_b128 v[162:165], v2 offset:3072
	s_mov_b32 m0, s49
	v_lshl_add_u64 v[208:209], v[210:211], 0, s[46:47]
	ds_read_b128 v[2:5], v215 offset:32768
	ds_read_b128 v[6:9], v215 offset:33792
	ds_read_b128 v[180:183], v215 offset:34816
	ds_read_b128 v[184:187], v215 offset:35840
	ds_read_b128 v[216:219], v215 offset:36864
	ds_read_b128 v[220:223], v215 offset:37888
	ds_read_b128 v[224:227], v215 offset:38912
	ds_read_b128 v[228:231], v215 offset:39936
	global_load_lds_dwordx4 v[208:209], off
	v_lshl_add_u64 v[208:209], v[210:211], 0, s[6:7]
	s_mov_b32 m0, s88
	s_nop 0
	global_load_lds_dwordx4 v[208:209], off
	v_lshl_add_u64 v[208:209], s[12:13], 0, v[192:193]
	s_mov_b32 m0, s89
	s_nop 0
	global_load_lds_dword v[208:209], off
	s_waitcnt vmcnt(9)
	s_waitcnt lgkmcnt(0)
	s_setprio 1
	s_barrier
	v_mfma_f32_16x16x32_bf16 v[134:137], v[146:149], v[2:5], v[134:137]
	v_mfma_f32_16x16x32_bf16 v[134:137], v[150:153], v[6:9], v[134:137]
	v_mfma_f32_16x16x32_bf16 v[130:133], v[158:161], v[6:9], v[130:133]
	v_mfma_f32_16x16x32_bf16 v[130:133], v[154:157], v[2:5], v[130:133]
	v_mfma_f32_16x16x32_bf16 v[122:125], v[154:157], v[180:183], v[122:125]
	v_mfma_f32_16x16x32_bf16 v[122:125], v[158:161], v[184:187], v[122:125]
	v_mfma_f32_16x16x32_bf16 v[126:129], v[150:153], v[184:187], v[126:129]
	v_mfma_f32_16x16x32_bf16 v[126:129], v[146:149], v[180:183], v[126:129]
	v_mfma_f32_16x16x32_bf16 v[114:117], v[146:149], v[216:219], v[114:117]
	v_mfma_f32_16x16x32_bf16 v[114:117], v[150:153], v[220:223], v[114:117]
	v_mfma_f32_16x16x32_bf16 v[106:109], v[158:161], v[220:223], v[106:109]
	v_mfma_f32_16x16x32_bf16 v[106:109], v[154:157], v[216:219], v[106:109]
	v_mfma_f32_16x16x32_bf16 v[90:93], v[154:157], v[224:227], v[90:93]
	v_mfma_f32_16x16x32_bf16 v[90:93], v[158:161], v[228:231], v[90:93]
	v_mfma_f32_16x16x32_bf16 v[98:101], v[150:153], v[228:231], v[98:101]
	v_mfma_f32_16x16x32_bf16 v[98:101], v[146:149], v[224:227], v[98:101]
	s_setprio 0
	s_setprio 1
	v_mfma_f32_16x16x32_bf16 v[118:121], v[166:169], v[2:5], v[118:121]
	v_mfma_f32_16x16x32_bf16 v[118:121], v[170:173], v[6:9], v[118:121]
	v_mfma_f32_16x16x32_bf16 v[2:5], v[174:177], v[2:5], v[110:113]
	v_mfma_f32_16x16x32_bf16 v[110:113], v[162:165], v[6:9], v[2:5]
	v_mfma_f32_16x16x32_bf16 v[2:5], v[166:169], v[180:183], v[102:105]
	v_mfma_f32_16x16x32_bf16 v[102:105], v[170:173], v[184:187], v[2:5]
	v_mfma_f32_16x16x32_bf16 v[2:5], v[174:177], v[180:183], v[94:97]
	v_mfma_f32_16x16x32_bf16 v[94:97], v[162:165], v[184:187], v[2:5]
	v_mfma_f32_16x16x32_bf16 v[2:5], v[166:169], v[216:219], v[86:89]
	v_mfma_f32_16x16x32_bf16 v[86:89], v[170:173], v[220:223], v[2:5]
	v_mfma_f32_16x16x32_bf16 v[2:5], v[174:177], v[216:219], v[82:85]
	v_mfma_f32_16x16x32_bf16 v[82:85], v[162:165], v[220:223], v[2:5]
	v_mfma_f32_16x16x32_bf16 v[2:5], v[166:169], v[224:227], v[78:81]
	v_mfma_f32_16x16x32_bf16 v[78:81], v[170:173], v[228:231], v[2:5]
	v_mfma_f32_16x16x32_bf16 v[2:5], v[174:177], v[224:227], v[74:77]
	v_mfma_f32_16x16x32_bf16 v[74:77], v[162:165], v[228:231], v[2:5]
	s_barrier
; #define PG8_SB(B) __builtin_amdgcn_rcpf(1.f + expneg(B))
; #define PG8_SB(B) __builtin_amdgcn_rcpf(1.f + expneg(B))
; #define PG8_STAGE(bufoff, gbase, voff) do { _Pragma("unroll") for (int _i = 0; _i < 2; ++_i) \
;         __builtin_amdgcn_global_load_lds((const unsigned*)((const char*)(gbase) + (size_t)_i * qstep + (voff)[0]), (PG8_LAS unsigned*)(lds + (bufoff) + ldsw + _i * 8192), 16, 0, 0); } while (0)
; #define PG8_LDA(dst, b, h) do { _Pragma("unroll") for (int m = 0; m < 4; ++m) _Pragma("unroll") for (int k = 0; k < 2; ++k) dst[m][k] = *(const PG8_LAS bf16x8*)(lds + PG8_SA(b, h) + aoff + m * 2048 + k * 1024); } while (0)
; #define PG8_MMA(ai, bj, At, Bt) do { __builtin_amdgcn_s_setprio(1); _Pragma("unroll") for (int m = 0; m < 4; ++m) _Pragma("unroll") for (int n = 0; n < 2; ++n) _Pragma("unroll") for (int k = 0; k < 2; ++k) \
;         acc[ai][bj][m][n] = __builtin_amdgcn_mfma_f32_16x16x32_bf16(Bt[n][k], At[m][k], acc[ai][bj][m][n], 0, 0, 0); __builtin_amdgcn_s_setprio(0); } while (0)
; #define PG8_WAIT_V89() do { if constexpr (SLIVER) PG8_WAIT_V(9); else PG8_WAIT_V(8); } while (0)
; #define PG8_LDS_S(b) do { if constexpr (SLIVER) { Sf[0] = *(const PG8_LAS bf16x8*)(lds + STAGE_BYTES + (b) * 2048 + soff0); Sf[1] = *(const PG8_LAS bf16x8*)(lds + STAGE_BYTES + (b) * 2048 + (soff0 ^ 64)); } } while (0)
; #define PG8_WAIT_L(n) asm volatile("s_waitcnt lgkmcnt(" #n ")" ::: "memory")
; #define PG8_BAR __builtin_amdgcn_s_barrier()
; #define PG8_SCHED __builtin_amdgcn_sched_barrier(0)
; template <class Epi, class Sched, bool ALIGN_EPI = false, bool SP2 = false, bool SLIVER = false>
; __device__ __forceinline__ void gemm_phase(PG8_LAS unsigned char* lds, const Gemm g, const Sched& S, const Epi& E) {
;     ...
;             PG8_LDA(At, 1, 1); PG8_LDS_S(1); PG8_STAGE(PG8_SB(1, 0), b3, voffB); PG8_STAGE(PG8_SB(1, 1), b3 + hstep, voffB); PG8_STAGE(PG8_SA(1, 0), a3, voffA);
;             PG8_WAIT_V89(); PG8_WAIT_L(0); PG8_BAR; PG8_MMA(1, 0, At, B0); PG8_MMA(1, 1, At, B1); PG8_MMA_S(); PG8_BAR; PG8_SCHED;
	s_setprio 0
	s_add_i32 s12, 0, 0x20800
	v_add_u32_e32 v178, s12, v213
	v_add_u32_e32 v184, s12, v214
	s_add_i32 s12, s68, s92
	v_lshl_add_u64 v[208:209], v[202:203], 0, s[26:27]
	s_mov_b32 m0, s12
	ds_read_b128 v[2:5], v215 offset:49152
	ds_read_b128 v[6:9], v215 offset:50176
	ds_read_b128 v[216:219], v215 offset:51200
	ds_read_b128 v[220:223], v215 offset:52224
	ds_read_b128 v[224:227], v215 offset:53248
	ds_read_b128 v[228:231], v215 offset:54272
	ds_read_b128 v[232:235], v215 offset:55296
	ds_read_b128 v[240:243], v215 offset:56320
	ds_read_b128 v[180:183], v178
	ds_read_b128 v[184:187], v184
	global_load_lds_dwordx4 v[208:209], off
	v_lshl_add_u64 v[208:209], v[202:203], 0, s[58:59]
	s_add_i32 m0, s12, 0x2000
	s_mov_b64 s[12:13], 0x90080
	global_load_lds_dwordx4 v[208:209], off
	v_lshl_add_u64 v[208:209], v[202:203], 0, s[12:13]
	s_add_i32 s12, s69, s92
	s_mov_b32 m0, s12
	s_mov_b64 s[68:69], 0xd8080
	global_load_lds_dwordx4 v[208:209], off
	v_lshl_add_u64 v[202:203], v[202:203], 0, s[68:69]
	s_add_i32 m0, s12, 0x2000
	s_nop 0
	global_load_lds_dwordx4 v[202:203], off
	v_lshl_add_u64 v[202:203], v[210:211], 0, s[26:27]
	s_mov_b32 m0, s51
	s_nop 0
	global_load_lds_dwordx4 v[202:203], off
	v_lshl_add_u64 v[202:203], v[210:211], 0, s[58:59]
	s_mov_b32 m0, s53
	s_nop 0
	global_load_lds_dwordx4 v[202:203], off
	s_waitcnt vmcnt(9)
	s_waitcnt lgkmcnt(0)
	s_setprio 1
	s_barrier
	v_mfma_f32_16x16x32_bf16 v[70:73], v[146:149], v[2:5], v[70:73]
	v_mfma_f32_16x16x32_bf16 v[70:73], v[150:153], v[6:9], v[70:73]
	v_mfma_f32_16x16x32_bf16 v[66:69], v[158:161], v[6:9], v[66:69]
	v_mfma_f32_16x16x32_bf16 v[66:69], v[154:157], v[2:5], v[66:69]
	v_mfma_f32_16x16x32_bf16 v[58:61], v[154:157], v[216:219], v[58:61]
	v_mfma_f32_16x16x32_bf16 v[58:61], v[158:161], v[220:223], v[58:61]
	v_mfma_f32_16x16x32_bf16 v[62:65], v[150:153], v[220:223], v[62:65]
	v_mfma_f32_16x16x32_bf16 v[62:65], v[146:149], v[216:219], v[62:65]
	v_mfma_f32_16x16x32_bf16 v[50:53], v[146:149], v[224:227], v[50:53]
	v_mfma_f32_16x16x32_bf16 v[50:53], v[150:153], v[228:231], v[50:53]
	v_mfma_f32_16x16x32_bf16 v[42:45], v[158:161], v[228:231], v[42:45]
	v_mfma_f32_16x16x32_bf16 v[42:45], v[154:157], v[224:227], v[42:45]
	v_mfma_f32_16x16x32_bf16 v[26:29], v[154:157], v[232:235], v[26:29]
	v_mfma_f32_16x16x32_bf16 v[26:29], v[158:161], v[240:243], v[26:29]
	v_mfma_f32_16x16x32_bf16 v[34:37], v[150:153], v[240:243], v[34:37]
	v_mfma_f32_16x16x32_bf16 v[34:37], v[146:149], v[232:235], v[34:37]
	s_setprio 0
	s_setprio 1
	v_mfma_f32_16x16x32_bf16 v[54:57], v[166:169], v[2:5], v[54:57]
	v_mfma_f32_16x16x32_bf16 v[54:57], v[170:173], v[6:9], v[54:57]
	v_mfma_f32_16x16x32_bf16 v[2:5], v[174:177], v[2:5], v[46:49]
	v_mfma_f32_16x16x32_bf16 v[46:49], v[162:165], v[6:9], v[2:5]
	v_mfma_f32_16x16x32_bf16 v[2:5], v[166:169], v[216:219], v[38:41]
	v_mfma_f32_16x16x32_bf16 v[38:41], v[170:173], v[220:223], v[2:5]
	v_mfma_f32_16x16x32_bf16 v[2:5], v[174:177], v[216:219], v[30:33]
	v_mfma_f32_16x16x32_bf16 v[30:33], v[162:165], v[220:223], v[2:5]
	v_mfma_f32_16x16x32_bf16 v[2:5], v[166:169], v[224:227], v[22:25]
	v_mfma_f32_16x16x32_bf16 v[22:25], v[170:173], v[228:231], v[2:5]
	v_mfma_f32_16x16x32_bf16 v[2:5], v[174:177], v[224:227], v[18:21]
	v_mfma_f32_16x16x32_bf16 v[18:21], v[162:165], v[228:231], v[2:5]
	v_mfma_f32_16x16x32_bf16 v[2:5], v[166:169], v[232:235], v[14:17]
	v_mfma_f32_16x16x32_bf16 v[14:17], v[170:173], v[240:243], v[2:5]
	v_mfma_f32_16x16x32_bf16 v[2:5], v[174:177], v[232:235], v[10:13]
	v_mfma_f32_16x16x32_bf16 v[10:13], v[162:165], v[240:243], v[2:5]
	s_setprio 0
	s_setprio 1
	s_and_b64 vcc, exec, s[90:91]
	s_cbranch_vccz .Lslv_c3
	v_mfma_f32_16x16x32_bf16 v[2:5], v[166:169], v[180:183], v[138:141]
	v_mfma_f32_16x16x32_bf16 v[6:9], v[170:173], v[184:187], v[2:5]
	v_mfma_f32_16x16x32_bf16 v[2:5], v[174:177], v[180:183], v[142:145]
	v_mfma_f32_16x16x32_bf16 v[2:5], v[162:165], v[184:187], v[2:5]
	s_barrier
	s_setprio 0
	s_branch .Lrot_c3
